# mixer: SSD-half streams 3 decode units before its scan; hand-written SSD and mLSTM decode streaming loops; GEMM epilogue ssq loads batched
# speedup vs baseline: 1.0147x; 1.0147x over previous
_Z10hybrid_fwd4Args:
	s_mov_b32 s98, 0
	s_load_dwordx2 s[12:13], s[0:1], 0xf0
	s_load_dwordx4 s[4:7], s[0:1], 0xe0
	s_waitcnt lgkmcnt(0)
	v_writelane_b32 v234, s4, 0
	s_nop 1
	v_writelane_b32 v234, s5, 1
	v_writelane_b32 v234, s6, 2
	v_writelane_b32 v234, s7, 3
	s_load_dwordx8 s[4:11], s[0:1], 0xc0
	s_waitcnt lgkmcnt(0)
	v_writelane_b32 v234, s4, 4
	s_nop 1
	v_writelane_b32 v234, s5, 5
	v_writelane_b32 v234, s6, 6
	v_writelane_b32 v234, s7, 7
	v_writelane_b32 v234, s8, 8
	v_writelane_b32 v234, s9, 9
	v_writelane_b32 v234, s10, 10
	v_writelane_b32 v234, s11, 11
	s_add_u32 s10, s0, 0xf0
	v_writelane_b32 v234, s12, 12
	s_addc_u32 s11, s1, 0
	s_and_b32 s4, s12, 7
	v_writelane_b32 v234, s13, 13
	s_cmp_lg_u32 s4, 0
	v_writelane_b32 v234, s2, 14
	v_writelane_b32 v234, s2, 15
	s_cbranch_scc1 .LBB0_2
	s_load_dwordx2 s[4:5], s[0:1], 0xf0
	v_readlane_b32 s2, v234, 14
	s_waitcnt lgkmcnt(0)
	s_ashr_i32 s5, s2, 31
	s_lshr_b32 s5, s5, 29
	s_add_i32 s5, s2, s5
	s_and_b32 s6, s5, -8
	s_ashr_i32 s4, s4, 3
	s_sub_i32 s6, s2, s6
	s_mul_i32 s4, s4, s6
	s_ashr_i32 s5, s5, 3
	s_add_i32 s4, s4, s5
	v_writelane_b32 v234, s4, 15

.LBB0_1714:
	s_or_b64 exec, exec, s[0:1]
	s_mov_b32 s98, 4
	s_branch .LBB0_2002

.Learly_chk:
	s_cmp_eq_u32 s98, 0
	s_cbranch_scc1 .Learly_go
.Learly_exit:
	s_mov_b32 s98, 0
	s_mov_b64 s[12:13], -1
	s_barrier
	s_branch .LBB0_1815

.LBB0_2007:
	s_cmp_lt_u32 s98, 2
	s_cbranch_scc1 .Learly_chk
	s_sub_u32 s98, s98, 1

.LBB0_2025:
	s_add_i32 s8, s20, 0xfffffe00
	v_mov_b32_e32 v8, v183
	s_lshr_b32 s24, s8, 2
	v_readfirstlane_b32 s9, v8
	s_lshl_b32 s8, s8, 3
	s_ashr_i32 s9, s9, 6
	s_and_b32 s8, s8, 24
	s_add_i32 s8, s9, s8
	s_or_b32 s14, s24, 0x2000
	s_lshl_b32 s9, s9, 11
	s_ashr_i32 s10, s8, 4
	s_add_i32 s11, s9, 0
	s_mul_i32 s21, s14, 0x1400
	v_readlane_b32 s22, v233, 21
	s_mul_hi_u32 s9, s14, 0x1400
	v_readlane_b32 s23, v233, 22
	s_add_u32 s22, s22, s21
	v_and_b32_e32 v71, 63, v8
	s_addc_u32 s23, s23, s9
	s_lshl_b32 s26, s8, 6
	v_or_b32_e32 v0, s26, v71
	v_ashrrev_i32_e32 v1, 31, v0
	v_lshl_add_u64 v[0:1], v[0:1], 1, s[22:23]
	global_load_ushort v12, v[0:1], off
	s_lshl_b32 s9, s10, 7
	s_add_i32 s21, s9, 0x800
	v_or_b32_e32 v0, s21, v71
	v_ashrrev_i32_e32 v1, 31, v0
	v_lshl_add_u64 v[0:1], v[0:1], 1, s[22:23]
	global_load_ushort v13, v[0:1], off
	global_load_ushort v14, v[0:1], off offset:128
	global_load_ushort v15, v[0:1], off offset:512
	global_load_ushort v16, v[0:1], off offset:640
	v_lshl_add_u32 v3, v71, 2, s11
	v_cmp_lt_i32_e32 vcc, v64, v149
	v_readlane_b32 s56, v234, 56
	v_readlane_b32 s57, v234, 57
	v_readlane_b32 s58, v234, 58
	v_readlane_b32 s59, v234, 59
	v_readlane_b32 s60, v234, 60
	v_readlane_b32 s61, v234, 61
	v_readlane_b32 s62, v234, 62
	v_readlane_b32 s63, v234, 63
	v_readlane_b32 s64, v233, 0
	v_readlane_b32 s65, v233, 1
	v_readlane_b32 s66, v233, 2
	v_readlane_b32 s67, v233, 3
	s_mov_b64 s[56:57], s[60:61]
	s_mov_b64 s[58:59], s[62:63]
	s_mov_b64 s[60:61], s[64:65]
	s_mov_b32 s25, s15
	v_readlane_b32 s68, v233, 4
	v_readlane_b32 s69, v233, 5
	v_readlane_b32 s70, v233, 6
	v_readlane_b32 s71, v233, 7
	s_mov_b64 s[62:63], s[66:67]
	v_mov_b32_e32 v78, 0
	s_waitcnt vmcnt(0)
	v_lshlrev_b32_e32 v2, 16, v12
	v_lshlrev_b32_e32 v0, 16, v13
	ds_write2st64_b32 v3, v2, v0 offset1:1
	v_lshlrev_b32_e32 v2, 16, v14
	v_lshlrev_b32_e32 v0, 16, v15
	ds_write2st64_b32 v3, v2, v0 offset0:2 offset1:3
	v_lshlrev_b32_e32 v0, 16, v16
	v_readlane_b32 s21, v233, 19
	s_ashr_i32 s9, s8, 31
	s_lshl_b64 s[22:23], s[14:15], 8
	s_add_u32 s21, s21, s22
	v_readlane_b32 s22, v233, 20
	s_addc_u32 s27, s22, s23
	s_lshl_b64 s[22:23], s[8:9], 2
	s_add_u32 s28, s21, s22
	s_addc_u32 s29, s27, s23
	ds_write_b32 v3, v0 offset:1024
	s_waitcnt lgkmcnt(0)
	ds_read2st64_b32 v[0:1], v3 offset0:3 offset1:4
	ds_read2st64_b32 v[2:3], v3 offset0:1 offset1:2
	s_waitcnt lgkmcnt(0)
	v_mul_f32_e32 v1, v1, v3
	v_fmac_f32_e32 v1, v0, v2
	v_cndmask_b32_e32 v0, v148, v64, vcc
	v_lshlrev_b32_e32 v72, 2, v0
	ds_bpermute_b32 v0, v72, v1
	v_cmp_lt_i32_e32 vcc, v65, v149
	s_waitcnt lgkmcnt(0)
	v_add_f32_e32 v0, v1, v0
	v_cndmask_b32_e32 v1, v148, v65, vcc
	v_lshlrev_b32_e32 v73, 2, v1
	ds_bpermute_b32 v1, v73, v0
	v_cmp_lt_i32_e32 vcc, v66, v149
	s_waitcnt lgkmcnt(0)
	v_add_f32_e32 v0, v0, v1
	v_cndmask_b32_e32 v1, v148, v66, vcc
	v_lshlrev_b32_e32 v74, 2, v1
	ds_bpermute_b32 v1, v74, v0
	v_cmp_lt_i32_e32 vcc, v67, v149
	s_waitcnt lgkmcnt(0)
	v_add_f32_e32 v0, v0, v1
	v_cndmask_b32_e32 v1, v148, v67, vcc
	v_lshlrev_b32_e32 v75, 2, v1
	ds_bpermute_b32 v1, v75, v0
	v_cmp_lt_i32_e32 vcc, v150, v149
	s_waitcnt lgkmcnt(0)
	v_add_f32_e32 v0, v0, v1
	v_cndmask_b32_e32 v1, v148, v150, vcc
	v_lshlrev_b32_e32 v76, 2, v1
	ds_bpermute_b32 v1, v76, v0
	v_cmp_lt_i32_e32 vcc, v151, v149
	s_waitcnt lgkmcnt(0)
	v_add_f32_e32 v0, v0, v1
	v_cndmask_b32_e32 v1, v148, v151, vcc
	v_lshlrev_b32_e32 v77, 2, v1
	ds_bpermute_b32 v1, v77, v0
	s_waitcnt lgkmcnt(0)
	v_add_f32_e32 v9, v0, v1
	global_load_dword v0, v37, s[28:29] offset:32
	s_add_u32 s28, s56, s22
	s_addc_u32 s29, s57, s23
	global_load_dword v1, v37, s[28:29]
	s_add_u32 s28, s58, s22
	s_addc_u32 s29, s59, s23
	s_add_u32 s22, s60, s22
	s_addc_u32 s23, s61, s23
	s_lshl_b64 s[8:9], s[8:9], 13
	v_readlane_b32 s56, v234, 24
	v_readlane_b32 s57, v234, 25
	v_readlane_b32 s58, v234, 26
	v_readlane_b32 s59, v234, 27
	v_readlane_b32 s68, v234, 36
	v_readlane_b32 s69, v234, 37
	v_readlane_b32 s56, v234, 0
	v_readlane_b32 s57, v234, 1
	v_readlane_b32 s60, v234, 28
	v_readlane_b32 s61, v234, 29
	v_readlane_b32 s62, v234, 30
	v_readlane_b32 s63, v234, 31
	v_readlane_b32 s64, v234, 32
	v_readlane_b32 s65, v234, 33
	v_readlane_b32 s66, v234, 34
	v_readlane_b32 s67, v234, 35
	v_readlane_b32 s70, v234, 38
	v_readlane_b32 s71, v234, 39
	v_readlane_b32 s58, v234, 2
	v_readlane_b32 s59, v234, 3
	global_load_dword v42, v37, s[22:23]
	s_lshl_b64 s[22:23], s[24:25], 18
	s_add_u32 s22, s8, s22
	s_addc_u32 s23, s9, s23
	s_ashr_i32 s27, s26, 31
	s_lshl_b64 s[22:23], s[22:23], 2
	s_lshl_b64 s[26:27], s[26:27], 1
	s_waitcnt vmcnt(1)
	v_add_f32_e32 v0, v0, v1
	v_max_f32_e32 v18, 0, v0
	v_mul_f32_e64 v0, |v0|, s47
	v_exp_f32_e32 v19, v0
	s_nop 0
	v_add_f32_e32 v2, 1.0, v19
	v_add_f32_e32 v0, -1.0, v2
	v_sub_f32_e32 v1, v0, v2
	v_add_f32_e32 v1, 1.0, v1
	v_sub_f32_e32 v0, v19, v0
	v_add_f32_e32 v3, v0, v1
	v_frexp_mant_f32_e32 v0, v2
	v_cmp_gt_f32_e32 vcc, s48, v0
	v_cvt_f64_f32_e32 v[0:1], v2
	v_frexp_exp_i32_f64_e32 v0, v[0:1]
	v_subbrev_co_u32_e32 v10, vcc, 0, v0, vcc
	v_sub_u32_e32 v0, 0, v10
	v_ldexp_f32 v1, v2, v0
	v_add_f32_e32 v2, -1.0, v1
	v_add_f32_e32 v4, 1.0, v1
	v_ldexp_f32 v0, v3, v0
	v_add_f32_e32 v3, 1.0, v2
	v_add_f32_e32 v5, -1.0, v4
	v_sub_f32_e32 v3, v1, v3
	v_sub_f32_e32 v1, v1, v5
	v_add_f32_e32 v3, v0, v3
	v_add_f32_e32 v0, v0, v1
	v_add_f32_e32 v11, v4, v0
	v_rcp_f32_e32 v13, v11
	v_sub_f32_e32 v1, v11, v4
	v_sub_f32_e32 v12, v0, v1
	v_add_f32_e32 v1, v2, v3
	v_mul_f32_e32 v15, v1, v13
	v_sub_f32_e32 v0, v1, v2
	v_mul_f32_e32 v2, v11, v15
	v_fma_f32 v4, v15, v11, -v2
	v_fmac_f32_e32 v4, v15, v12
	v_sub_f32_e32 v14, v3, v0
	v_add_f32_e32 v0, v2, v4
	v_sub_f32_e32 v3, v1, v0
	v_pk_add_f32 v[6:7], v[0:1], v[2:3] neg_lo:[0,1] neg_hi:[0,1]
	v_mov_b32_e32 v5, v0
	v_pk_add_f32 v[0:1], v[6:7], v[4:5] neg_lo:[0,1] neg_hi:[0,1]
	v_cmp_neq_f32_e32 vcc, s50, v19
	v_add_f32_e32 v1, v14, v1
	v_add_f32_e32 v0, v0, v1
	v_add_f32_e32 v1, v3, v0
	v_mul_f32_e32 v14, v13, v1
	v_mul_f32_e32 v2, v11, v14
	v_fma_f32 v4, v14, v11, -v2
	v_fmac_f32_e32 v4, v14, v12
	v_sub_f32_e32 v3, v3, v1
	v_add_f32_e32 v11, v0, v3
	v_add_f32_e32 v0, v2, v4
	v_sub_f32_e32 v3, v1, v0
	v_pk_add_f32 v[6:7], v[0:1], v[2:3] neg_lo:[0,1] neg_hi:[0,1]
	v_mov_b32_e32 v5, v0
	v_pk_add_f32 v[0:1], v[6:7], v[4:5] neg_lo:[0,1] neg_hi:[0,1]
	s_nop 0
	v_add_f32_e32 v1, v11, v1
	v_add_f32_e32 v0, v0, v1
	v_add_f32_e32 v1, v15, v14
	v_add_f32_e32 v0, v3, v0
	v_sub_f32_e32 v2, v1, v15
	v_mul_f32_e32 v0, v13, v0
	v_sub_f32_e32 v2, v14, v2
	v_add_f32_e32 v2, v2, v0
	v_add_f32_e32 v4, v1, v2
	v_mul_f32_e32 v5, v4, v4
	v_fmamk_f32 v0, v5, 0x3e9b6dac, v62
	v_fmaak_f32 v39, v5, v0, 0x3f2aaada
	v_cvt_f32_i32_e32 v0, v10
	v_sub_f32_e32 v1, v4, v1
	v_sub_f32_e32 v1, v2, v1
	v_ldexp_f32 v6, v1, 1
	v_mul_f32_e32 v1, v4, v5
	v_ldexp_f32 v3, v4, 1
	v_pk_mul_f32 v[4:5], v[0:1], v[38:39]
	s_nop 0
	v_fma_f32 v2, v0, s49, -v4
	v_fmac_f32_e32 v2, 0xb102e308, v0
	v_pk_add_f32 v[0:1], v[4:5], v[2:3]
	s_nop 0
	v_sub_f32_e32 v3, v1, v3
	v_sub_f32_e32 v3, v5, v3
	v_add_f32_e32 v7, v6, v3
	v_mov_b32_e32 v6, v4
	v_pk_add_f32 v[4:5], v[0:1], v[4:5] neg_lo:[0,1] neg_hi:[0,1]
	v_pk_add_f32 v[10:11], v[0:1], v[6:7]
	v_mov_b32_e32 v3, v0
	v_mov_b32_e32 v5, v11
	v_pk_add_f32 v[12:13], v[2:3], v[4:5] neg_lo:[0,1] neg_hi:[0,1]
	v_pk_add_f32 v[2:3], v[2:3], v[4:5]
	v_mov_b32_e32 v16, v1
	v_pk_add_f32 v[4:5], v[2:3], v[0:1] op_sel:[1,0] op_sel_hi:[0,1] neg_lo:[0,1] neg_hi:[0,1]
	v_pk_add_f32 v[14:15], v[10:11], v[4:5] op_sel_hi:[1,0] neg_lo:[0,1] neg_hi:[0,1]
	v_mov_b32_e32 v10, v11
	v_mov_b32_e32 v11, v3
	v_mov_b32_e32 v17, v4
	v_pk_add_f32 v[4:5], v[10:11], v[16:17] neg_lo:[0,1] neg_hi:[0,1]
	v_mov_b32_e32 v6, v7
	v_mov_b32_e32 v7, v0
	v_pk_add_f32 v[0:1], v[6:7], v[4:5] neg_lo:[0,1] neg_hi:[0,1]
	v_mov_b32_e32 v14, v12
	v_pk_add_f32 v[4:5], v[14:15], v[0:1]
	v_mov_b32_e32 v13, v3
	v_pk_add_f32 v[6:7], v[4:5], v[4:5] op_sel:[0,1] op_sel_hi:[1,0]
	s_nop 0
	v_pk_add_f32 v[2:3], v[2:3], v[6:7] op_sel:[1,0] op_sel_hi:[0,1]
	v_mov_b32_e32 v5, v2
	v_pk_add_f32 v[10:11], v[4:5], v[12:13] neg_lo:[0,1] neg_hi:[0,1]
	v_mov_b32_e32 v1, v6
	v_sub_f32_e32 v3, v4, v10
	v_pk_add_f32 v[0:1], v[0:1], v[10:11] neg_lo:[0,1] neg_hi:[0,1]
	v_sub_f32_e32 v3, v12, v3
	v_add_f32_e32 v0, v0, v3
	v_add_f32_e32 v0, v0, v1
	v_add_f32_e32 v0, v2, v0
	v_cndmask_b32_e32 v0, v68, v0, vcc
	v_cmp_ngt_f32_e32 vcc, -1.0, v19
	v_and_b32_e32 v10, 31, v8
	v_bfe_u32 v11, v8, 5, 1
	v_cndmask_b32_e32 v0, v69, v0, vcc
	v_cmp_neq_f32_e32 vcc, -1.0, v19
	v_lshlrev_b32_e32 v12, 4, v10
	v_add_u32_e32 v4, s11, v12
	v_cndmask_b32_e32 v0, v70, v0, vcc
	v_cmp_lt_f32_e64 vcc, |v19|, s51
	v_lshl_add_u32 v79, v11, 2, s11
	v_lshlrev_b32_e32 v8, 4, v8
	v_cndmask_b32_e32 v0, v0, v19, vcc
	v_add_f32_e32 v39, v18, v0
	global_load_dword v0, v37, s[28:29]
	s_movk_i32 s11, 0x200
	s_lshl_b64 s[28:29], s[24:25], 12
	v_and_or_b32 v36, v8, s11, v12
	s_add_u32 s11, s38, s26
	s_addc_u32 s21, s39, s27
	s_add_u32 s28, s11, s28
	s_addc_u32 s29, s21, s29
	s_mul_hi_u32 s11, s24, 0x7400
	s_mul_i32 s21, s24, 0x7400
	s_add_u32 s24, s40, s26
	s_addc_u32 s25, s41, s27
	v_lshl_add_u64 v[48:49], s[68:69], 0, v[36:37]
	v_lshl_or_b32 v36, v11, 9, v12
	s_add_u32 s24, s24, s21
	v_lshl_add_u64 v[50:51], s[56:57], 0, v[36:37]
	v_lshlrev_b32_e32 v36, 1, v11
	s_addc_u32 s25, s25, s11
	v_cmp_eq_u32_e64 s[8:9], 0, v10
	v_mul_f32_e32 v46, v9, v39
	v_lshl_add_u64 v[52:53], s[28:29], 0, v[36:37]
	v_lshl_add_u64 v[54:55], s[24:25], 0, v[36:37]
	s_mov_b32 s11, -8
	s_waitcnt vmcnt(0)
	v_mul_f32_e32 v0, 0x3fb8aa3b, v0
	v_exp_f32_e32 v0, v0
	s_nop 0
	v_mul_f32_e32 v0, v0, v39
	v_mul_f32_e32 v0, 0xbfb8aa3b, v0
	v_exp_f32_e32 v40, v0
	ds_read_b128 v[0:3], v4 offset:256
	ds_read_b128 v[4:7], v4 offset:768
	v_mov_b32_e32 v44, v40
	v_mov_b32_e32 v45, v40
	v_mov_b32_e32 v47, v40
	s_mov_b64 s[26:27], 0x1000
	v_readlane_b32 s28, v54, 0
	v_readlane_b32 s29, v55, 0
	v_readlane_b32 s56, v52, 0
	v_readlane_b32 s57, v53, 0
	v_readlane_b32 s58, v79, 0
	v_mov_b32_e32 v41, v40
	v_and_b32_e32 v86, 31, v71
	v_lshrrev_b32_e32 v87, 5, v71
	v_lshlrev_b32_e32 v237, 4, v87
	v_sub_u32_e32 v237, 16, v237
	v_lshlrev_b32_e32 v239, 2, v86
	v_lshl_add_u64 v[240:241], v[48:49], 0, s[22:23]
	v_lshl_add_u64 v[242:243], v[50:51], 0, s[22:23]
	s_mov_b32 s24, 0x15162840
	s_mov_b32 s25, 0
	v_lshl_add_u64 v[242:243], v[242:243], 0, s[24:25]
	v_lshl_add_u32 v238, v87, 1, s58
	v_add_u32_e32 v238, 0x500, v238
	global_load_dword v236, v239, s[28:29] offset:-16
	global_load_dwordx4 v[80:83], v[240:241], off nt
	global_load_dwordx4 v[32:35], v[240:241], off offset:1024 nt
	global_load_dwordx4 v[28:31], v[240:241], off offset:2048 nt
	global_load_dwordx4 v[24:27], v[240:241], off offset:3072 nt
	v_lshl_add_u64 v[60:61], v[240:241], 0, s[26:27]
	global_load_dwordx4 v[20:23], v[60:61], off nt
	global_load_dwordx4 v[16:19], v[60:61], off offset:1024 nt
	global_load_dwordx4 v[12:15], v[60:61], off offset:2048 nt
	global_load_dwordx4 v[8:11], v[60:61], off offset:3072 nt
	s_mov_b32 s21, 0
.Lsd_loop:
	ds_read2_b32 v[244:245], v79 offset1:2
	ds_read2_b32 v[246:247], v79 offset0:4 offset1:6
	ds_read2_b32 v[248:249], v79 offset0:8 offset1:10
	ds_read2_b32 v[250:251], v79 offset0:12 offset1:14
	v_lshl_add_u64 v[88:89], v[242:243], 0, s[26:27]
	s_waitcnt lgkmcnt(0)
	s_waitcnt vmcnt(7)
	v_mul_f32_e32 v36, v39, v244
	v_mul_f32_e32 v252, v5, v81
	v_mul_f32_e32 v43, v7, v83
	v_pk_mul_f32 v[56:57], v[0:1], v[36:37] op_sel_hi:[1,0]
	v_pk_mul_f32 v[58:59], v[2:3], v[36:37] op_sel_hi:[1,0]
	v_fmac_f32_e32 v252, v4, v80
	v_fmac_f32_e32 v43, v6, v82
	v_pk_fma_f32 v[80:81], v[44:45], v[80:81], v[56:57]
	v_pk_fma_f32 v[82:83], v[40:41], v[82:83], v[58:59]
	v_add_f32_e32 v252, v252, v43
	global_store_dwordx4 v[242:243], v[80:83], off nt
	s_waitcnt vmcnt(7)
	v_mul_f32_e32 v36, v39, v245
	v_mul_f32_e32 v253, v5, v33
	v_mul_f32_e32 v43, v7, v35
	v_pk_mul_f32 v[56:57], v[0:1], v[36:37] op_sel_hi:[1,0]
	v_pk_mul_f32 v[58:59], v[2:3], v[36:37] op_sel_hi:[1,0]
	v_fmac_f32_e32 v253, v4, v32
	v_fmac_f32_e32 v43, v6, v34
	v_pk_fma_f32 v[32:33], v[44:45], v[32:33], v[56:57]
	v_pk_fma_f32 v[34:35], v[40:41], v[34:35], v[58:59]
	v_add_f32_e32 v253, v253, v43
	global_store_dwordx4 v[242:243], v[32:35], off offset:1024 nt
	s_waitcnt vmcnt(7)
	v_mul_f32_e32 v36, v39, v246
	v_mul_f32_e32 v254, v5, v29
	v_mul_f32_e32 v43, v7, v31
	v_pk_mul_f32 v[56:57], v[0:1], v[36:37] op_sel_hi:[1,0]
	v_pk_mul_f32 v[58:59], v[2:3], v[36:37] op_sel_hi:[1,0]
	v_fmac_f32_e32 v254, v4, v28
	v_fmac_f32_e32 v43, v6, v30
	v_pk_fma_f32 v[28:29], v[44:45], v[28:29], v[56:57]
	v_pk_fma_f32 v[30:31], v[40:41], v[30:31], v[58:59]
	v_add_f32_e32 v254, v254, v43
	global_store_dwordx4 v[242:243], v[28:31], off offset:2048 nt
	s_waitcnt vmcnt(7)
	v_mul_f32_e32 v36, v39, v247
	v_mul_f32_e32 v255, v5, v25
	v_mul_f32_e32 v43, v7, v27
	v_pk_mul_f32 v[56:57], v[0:1], v[36:37] op_sel_hi:[1,0]
	v_pk_mul_f32 v[58:59], v[2:3], v[36:37] op_sel_hi:[1,0]
	v_fmac_f32_e32 v255, v4, v24
	v_fmac_f32_e32 v43, v6, v26
	v_pk_fma_f32 v[24:25], v[44:45], v[24:25], v[56:57]
	v_pk_fma_f32 v[26:27], v[40:41], v[26:27], v[58:59]
	v_add_f32_e32 v255, v255, v43
	global_store_dwordx4 v[242:243], v[24:27], off offset:3072 nt
	s_waitcnt vmcnt(7)
	v_mul_f32_e32 v36, v39, v248
	v_mul_f32_e32 v90, v5, v21
	v_mul_f32_e32 v43, v7, v23
	v_pk_mul_f32 v[56:57], v[0:1], v[36:37] op_sel_hi:[1,0]
	v_pk_mul_f32 v[58:59], v[2:3], v[36:37] op_sel_hi:[1,0]
	v_fmac_f32_e32 v90, v4, v20
	v_fmac_f32_e32 v43, v6, v22
	v_pk_fma_f32 v[20:21], v[44:45], v[20:21], v[56:57]
	v_pk_fma_f32 v[22:23], v[40:41], v[22:23], v[58:59]
	v_add_f32_e32 v90, v90, v43
	global_store_dwordx4 v[88:89], v[20:23], off nt
	s_waitcnt vmcnt(7)
	v_mul_f32_e32 v36, v39, v249
	v_mul_f32_e32 v91, v5, v17
	v_mul_f32_e32 v43, v7, v19
	v_pk_mul_f32 v[56:57], v[0:1], v[36:37] op_sel_hi:[1,0]
	v_pk_mul_f32 v[58:59], v[2:3], v[36:37] op_sel_hi:[1,0]
	v_fmac_f32_e32 v91, v4, v16
	v_fmac_f32_e32 v43, v6, v18
	v_pk_fma_f32 v[16:17], v[44:45], v[16:17], v[56:57]
	v_pk_fma_f32 v[18:19], v[40:41], v[18:19], v[58:59]
	v_add_f32_e32 v91, v91, v43
	global_store_dwordx4 v[88:89], v[16:19], off offset:1024 nt
	s_waitcnt vmcnt(7)
	v_mul_f32_e32 v36, v39, v250
	v_mul_f32_e32 v92, v5, v13
	v_mul_f32_e32 v43, v7, v15
	v_pk_mul_f32 v[56:57], v[0:1], v[36:37] op_sel_hi:[1,0]
	v_pk_mul_f32 v[58:59], v[2:3], v[36:37] op_sel_hi:[1,0]
	v_fmac_f32_e32 v92, v4, v12
	v_fmac_f32_e32 v43, v6, v14
	v_pk_fma_f32 v[12:13], v[44:45], v[12:13], v[56:57]
	v_pk_fma_f32 v[14:15], v[40:41], v[14:15], v[58:59]
	v_add_f32_e32 v92, v92, v43
	global_store_dwordx4 v[88:89], v[12:15], off offset:2048 nt
	s_waitcnt vmcnt(7)
	v_mul_f32_e32 v36, v39, v251
	v_mul_f32_e32 v93, v5, v9
	v_mul_f32_e32 v43, v7, v11
	v_pk_mul_f32 v[56:57], v[0:1], v[36:37] op_sel_hi:[1,0]
	v_pk_mul_f32 v[58:59], v[2:3], v[36:37] op_sel_hi:[1,0]
	v_fmac_f32_e32 v93, v4, v8
	v_fmac_f32_e32 v43, v6, v10
	v_pk_fma_f32 v[8:9], v[44:45], v[8:9], v[56:57]
	v_pk_fma_f32 v[10:11], v[40:41], v[10:11], v[58:59]
	v_add_f32_e32 v93, v93, v43
	global_store_dwordx4 v[88:89], v[8:11], off offset:3072 nt
	v_lshl_add_u64 v[240:241], v[240:241], 0, s[16:17]
	v_lshl_add_u64 v[242:243], v[242:243], 0, s[16:17]
	v_add_u32_e32 v79, 64, v79
	s_cmp_eq_u32 s21, 24
	s_cbranch_scc1 .Lsd_nopf
	global_load_dwordx4 v[80:83], v[240:241], off nt
	global_load_dwordx4 v[32:35], v[240:241], off offset:1024 nt
	global_load_dwordx4 v[28:31], v[240:241], off offset:2048 nt
	global_load_dwordx4 v[24:27], v[240:241], off offset:3072 nt
	v_lshl_add_u64 v[60:61], v[240:241], 0, s[26:27]
	global_load_dwordx4 v[20:23], v[60:61], off nt
	global_load_dwordx4 v[16:19], v[60:61], off offset:1024 nt
	global_load_dwordx4 v[12:15], v[60:61], off offset:2048 nt
	global_load_dwordx4 v[8:11], v[60:61], off offset:3072 nt
.Lsd_nopf:
	ds_bpermute_b32 v56, v72, v252
	ds_bpermute_b32 v57, v72, v253
	ds_bpermute_b32 v58, v72, v254
	ds_bpermute_b32 v59, v72, v255
	ds_bpermute_b32 v60, v72, v90
	ds_bpermute_b32 v61, v72, v91
	ds_bpermute_b32 v84, v72, v92
	ds_bpermute_b32 v85, v72, v93
	s_waitcnt lgkmcnt(7)
	v_add_f32_e32 v252, v252, v56
	s_waitcnt lgkmcnt(6)
	v_add_f32_e32 v253, v253, v57
	s_waitcnt lgkmcnt(5)
	v_add_f32_e32 v254, v254, v58
	s_waitcnt lgkmcnt(4)
	v_add_f32_e32 v255, v255, v59
	s_waitcnt lgkmcnt(3)
	v_add_f32_e32 v90, v90, v60
	s_waitcnt lgkmcnt(2)
	v_add_f32_e32 v91, v91, v61
	s_waitcnt lgkmcnt(1)
	v_add_f32_e32 v92, v92, v84
	s_waitcnt lgkmcnt(0)
	v_add_f32_e32 v93, v93, v85
	ds_bpermute_b32 v56, v73, v252
	ds_bpermute_b32 v57, v73, v253
	ds_bpermute_b32 v58, v73, v254
	ds_bpermute_b32 v59, v73, v255
	ds_bpermute_b32 v60, v73, v90
	ds_bpermute_b32 v61, v73, v91
	ds_bpermute_b32 v84, v73, v92
	ds_bpermute_b32 v85, v73, v93
	s_waitcnt lgkmcnt(7)
	v_add_f32_e32 v252, v252, v56
	s_waitcnt lgkmcnt(6)
	v_add_f32_e32 v253, v253, v57
	s_waitcnt lgkmcnt(5)
	v_add_f32_e32 v254, v254, v58
	s_waitcnt lgkmcnt(4)
	v_add_f32_e32 v255, v255, v59
	s_waitcnt lgkmcnt(3)
	v_add_f32_e32 v90, v90, v60
	s_waitcnt lgkmcnt(2)
	v_add_f32_e32 v91, v91, v61
	s_waitcnt lgkmcnt(1)
	v_add_f32_e32 v92, v92, v84
	s_waitcnt lgkmcnt(0)
	v_add_f32_e32 v93, v93, v85
	ds_bpermute_b32 v56, v74, v252
	ds_bpermute_b32 v57, v74, v253
	ds_bpermute_b32 v58, v74, v254
	ds_bpermute_b32 v59, v74, v255
	ds_bpermute_b32 v60, v74, v90
	ds_bpermute_b32 v61, v74, v91
	ds_bpermute_b32 v84, v74, v92
	ds_bpermute_b32 v85, v74, v93
	s_waitcnt lgkmcnt(7)
	v_add_f32_e32 v252, v252, v56
	s_waitcnt lgkmcnt(6)
	v_add_f32_e32 v253, v253, v57
	s_waitcnt lgkmcnt(5)
	v_add_f32_e32 v254, v254, v58
	s_waitcnt lgkmcnt(4)
	v_add_f32_e32 v255, v255, v59
	s_waitcnt lgkmcnt(3)
	v_add_f32_e32 v90, v90, v60
	s_waitcnt lgkmcnt(2)
	v_add_f32_e32 v91, v91, v61
	s_waitcnt lgkmcnt(1)
	v_add_f32_e32 v92, v92, v84
	s_waitcnt lgkmcnt(0)
	v_add_f32_e32 v93, v93, v85
	ds_bpermute_b32 v56, v75, v252
	ds_bpermute_b32 v57, v75, v253
	ds_bpermute_b32 v58, v75, v254
	ds_bpermute_b32 v59, v75, v255
	ds_bpermute_b32 v60, v75, v90
	ds_bpermute_b32 v61, v75, v91
	ds_bpermute_b32 v84, v75, v92
	ds_bpermute_b32 v85, v75, v93
	s_waitcnt lgkmcnt(7)
	v_add_f32_e32 v252, v252, v56
	s_waitcnt lgkmcnt(6)
	v_add_f32_e32 v253, v253, v57
	s_waitcnt lgkmcnt(5)
	v_add_f32_e32 v254, v254, v58
	s_waitcnt lgkmcnt(4)
	v_add_f32_e32 v255, v255, v59
	s_waitcnt lgkmcnt(3)
	v_add_f32_e32 v90, v90, v60
	s_waitcnt lgkmcnt(2)
	v_add_f32_e32 v91, v91, v61
	s_waitcnt lgkmcnt(1)
	v_add_f32_e32 v92, v92, v84
	s_waitcnt lgkmcnt(0)
	v_add_f32_e32 v93, v93, v85
	ds_bpermute_b32 v56, v76, v252
	ds_bpermute_b32 v57, v76, v253
	ds_bpermute_b32 v58, v76, v254
	ds_bpermute_b32 v59, v76, v255
	ds_bpermute_b32 v60, v76, v90
	ds_bpermute_b32 v61, v76, v91
	ds_bpermute_b32 v84, v76, v92
	ds_bpermute_b32 v85, v76, v93
	s_waitcnt lgkmcnt(7)
	v_add_f32_e32 v252, v252, v56
	s_waitcnt lgkmcnt(6)
	v_add_f32_e32 v253, v253, v57
	s_waitcnt lgkmcnt(5)
	v_add_f32_e32 v254, v254, v58
	s_waitcnt lgkmcnt(4)
	v_add_f32_e32 v255, v255, v59
	s_waitcnt lgkmcnt(3)
	v_add_f32_e32 v90, v90, v60
	s_waitcnt lgkmcnt(2)
	v_add_f32_e32 v91, v91, v61
	s_waitcnt lgkmcnt(1)
	v_add_f32_e32 v92, v92, v84
	s_waitcnt lgkmcnt(0)
	v_add_f32_e32 v93, v93, v85
	v_readlane_b32 s60, v236, s21
	s_add_i32 s24, s21, 1
	v_readlane_b32 s61, v236, s24
	s_add_i32 s24, s21, 2
	v_readlane_b32 s62, v236, s24
	s_add_i32 s24, s21, 3
	v_readlane_b32 s63, v236, s24
	s_add_i32 s24, s21, 4
	v_readlane_b32 s64, v236, s24
	s_add_i32 s24, s21, 5
	v_readlane_b32 s65, v236, s24
	s_add_i32 s24, s21, 6
	v_readlane_b32 s66, v236, s24
	s_add_i32 s24, s21, 7
	v_readlane_b32 s67, v236, s24
	s_and_saveexec_b64 s[24:25], s[8:9]
	s_nop 1
	v_lshlrev_b32_e64 v56, v237, s60
	v_lshlrev_b32_e64 v60, v237, s61
	v_and_b32_e32 v56, 0xffff0000, v56
	v_and_b32_e32 v60, 0xffff0000, v60
	v_mul_f32_e32 v57, 0xbfb8aa3b, v56
	v_mul_f32_e32 v61, 0xbfb8aa3b, v60
	v_exp_f32_e32 v57, v57
	v_exp_f32_e32 v61, v61
	v_mul_f32_e32 v58, v46, v244
	v_mul_f32_e32 v84, v46, v245
	v_add_f32_e32 v57, 1.0, v57
	v_add_f32_e32 v61, 1.0, v61
	v_mul_f32_e32 v59, v47, v252
	v_mul_f32_e32 v85, v47, v253
	v_rcp_f32_e32 v57, v57
	v_rcp_f32_e32 v61, v61
	v_add_f32_e32 v58, v58, v59
	v_add_f32_e32 v84, v84, v85
	v_mul_f32_e32 v59, v42, v244
	v_mul_f32_e32 v85, v42, v245
	v_mul_f32_e32 v57, v57, v56
	v_mul_f32_e32 v61, v61, v60
	v_add_f32_e32 v58, v59, v58
	v_add_f32_e32 v84, v85, v84
	v_mul_f32_e32 v58, v58, v57
	v_mul_f32_e32 v84, v84, v61
	v_cvt_pk_bf16_f32 v59, v58, v58
	v_cvt_pk_bf16_f32 v85, v84, v84
	v_fmac_f32_e32 v78, v58, v58
	v_fmac_f32_e32 v78, v84, v84
	ds_write_b16 v238, v59 offset:0
	ds_write_b16 v238, v85 offset:4
	v_lshlrev_b32_e64 v56, v237, s62
	v_lshlrev_b32_e64 v60, v237, s63
	v_and_b32_e32 v56, 0xffff0000, v56
	v_and_b32_e32 v60, 0xffff0000, v60
	v_mul_f32_e32 v57, 0xbfb8aa3b, v56
	v_mul_f32_e32 v61, 0xbfb8aa3b, v60
	v_exp_f32_e32 v57, v57
	v_exp_f32_e32 v61, v61
	v_mul_f32_e32 v58, v46, v246
	v_mul_f32_e32 v84, v46, v247
	v_add_f32_e32 v57, 1.0, v57
	v_add_f32_e32 v61, 1.0, v61
	v_mul_f32_e32 v59, v47, v254
	v_mul_f32_e32 v85, v47, v255
	v_rcp_f32_e32 v57, v57
	v_rcp_f32_e32 v61, v61
	v_add_f32_e32 v58, v58, v59
	v_add_f32_e32 v84, v84, v85
	v_mul_f32_e32 v59, v42, v246
	v_mul_f32_e32 v85, v42, v247
	v_mul_f32_e32 v57, v57, v56
	v_mul_f32_e32 v61, v61, v60
	v_add_f32_e32 v58, v59, v58
	v_add_f32_e32 v84, v85, v84
	v_mul_f32_e32 v58, v58, v57
	v_mul_f32_e32 v84, v84, v61
	v_cvt_pk_bf16_f32 v59, v58, v58
	v_cvt_pk_bf16_f32 v85, v84, v84
	v_fmac_f32_e32 v78, v58, v58
	v_fmac_f32_e32 v78, v84, v84
	ds_write_b16 v238, v59 offset:8
	ds_write_b16 v238, v85 offset:12
	v_lshlrev_b32_e64 v56, v237, s64
	v_lshlrev_b32_e64 v60, v237, s65
	v_and_b32_e32 v56, 0xffff0000, v56
	v_and_b32_e32 v60, 0xffff0000, v60
	v_mul_f32_e32 v57, 0xbfb8aa3b, v56
	v_mul_f32_e32 v61, 0xbfb8aa3b, v60
	v_exp_f32_e32 v57, v57
	v_exp_f32_e32 v61, v61
	v_mul_f32_e32 v58, v46, v248
	v_mul_f32_e32 v84, v46, v249
	v_add_f32_e32 v57, 1.0, v57
	v_add_f32_e32 v61, 1.0, v61
	v_mul_f32_e32 v59, v47, v90
	v_mul_f32_e32 v85, v47, v91
	v_rcp_f32_e32 v57, v57
	v_rcp_f32_e32 v61, v61
	v_add_f32_e32 v58, v58, v59
	v_add_f32_e32 v84, v84, v85
	v_mul_f32_e32 v59, v42, v248
	v_mul_f32_e32 v85, v42, v249
	v_mul_f32_e32 v57, v57, v56
	v_mul_f32_e32 v61, v61, v60
	v_add_f32_e32 v58, v59, v58
	v_add_f32_e32 v84, v85, v84
	v_mul_f32_e32 v58, v58, v57
	v_mul_f32_e32 v84, v84, v61
	v_cvt_pk_bf16_f32 v59, v58, v58
	v_cvt_pk_bf16_f32 v85, v84, v84
	v_fmac_f32_e32 v78, v58, v58
	v_fmac_f32_e32 v78, v84, v84
	ds_write_b16 v238, v59 offset:16
	ds_write_b16 v238, v85 offset:20
	v_lshlrev_b32_e64 v56, v237, s66
	v_lshlrev_b32_e64 v60, v237, s67
	v_and_b32_e32 v56, 0xffff0000, v56
	v_and_b32_e32 v60, 0xffff0000, v60
	v_mul_f32_e32 v57, 0xbfb8aa3b, v56
	v_mul_f32_e32 v61, 0xbfb8aa3b, v60
	v_exp_f32_e32 v57, v57
	v_exp_f32_e32 v61, v61
	v_mul_f32_e32 v58, v46, v250
	v_mul_f32_e32 v84, v46, v251
	v_add_f32_e32 v57, 1.0, v57
	v_add_f32_e32 v61, 1.0, v61
	v_mul_f32_e32 v59, v47, v92
	v_mul_f32_e32 v85, v47, v93
	v_rcp_f32_e32 v57, v57
	v_rcp_f32_e32 v61, v61
	v_add_f32_e32 v58, v58, v59
	v_add_f32_e32 v84, v84, v85
	v_mul_f32_e32 v59, v42, v250
	v_mul_f32_e32 v85, v42, v251
	v_mul_f32_e32 v57, v57, v56
	v_mul_f32_e32 v61, v61, v60
	v_add_f32_e32 v58, v59, v58
	v_add_f32_e32 v84, v85, v84
	v_mul_f32_e32 v58, v58, v57
	v_mul_f32_e32 v84, v84, v61
	v_cvt_pk_bf16_f32 v59, v58, v58
	v_cvt_pk_bf16_f32 v85, v84, v84
	v_fmac_f32_e32 v78, v58, v58
	v_fmac_f32_e32 v78, v84, v84
	ds_write_b16 v238, v59 offset:24
	ds_write_b16 v238, v85 offset:28
	s_mov_b64 exec, s[24:25]
	v_add_u32_e32 v238, 32, v238
	s_add_i32 s21, s21, 8
	s_cmp_lt_u32 s21, 32
	s_cbranch_scc1 .Lsd_loop
	v_lshl_add_u32 v56, v71, 2, s58
	s_waitcnt lgkmcnt(0)
	ds_read_b32 v57, v56 offset:1280
	v_lshlrev_b32_e32 v56, 2, v71
	v_cmp_gt_u32_e32 vcc, 32, v71
	s_and_saveexec_b64 s[24:25], vcc
	s_waitcnt lgkmcnt(0)
	global_store_dword v56, v57, s[56:57] offset:-16
	s_mov_b64 exec, s[24:25]

.LBB0_2058:
	s_or_b64 exec, exec, s[22:23]
	s_lshl_b64 s[22:23], s[2:3], 8
	v_readlane_b32 s21, v233, 19
	s_add_u32 s22, s21, s22
	v_readlane_b32 s21, v233, 20
	s_addc_u32 s23, s21, s23
	s_lshl_b32 s21, s28, 2
	v_readlane_b32 s52, v234, 40
	v_mov_b32_e32 v8, s21
	v_readlane_b32 s62, v234, 50
	v_readlane_b32 s63, v234, 51
	s_waitcnt lgkmcnt(0)
	s_barrier
	ds_read_b128 v[4:7], v37 offset:5120
	ds_read_b128 v[0:3], v37 offset:5152
	global_load_dword v9, v8, s[22:23]
	global_load_dword v10, v8, s[62:63]
	v_readlane_b32 s56, v234, 44
	v_readlane_b32 s57, v234, 45
	v_readlane_b32 s58, v234, 46
	v_readlane_b32 s59, v234, 47
	v_readlane_b32 s64, v234, 52
	v_readlane_b32 s65, v234, 53
	v_readlane_b32 s66, v234, 54
	v_readlane_b32 s67, v234, 55
	s_mov_b64 s[56:57], s[64:65]
	v_readlane_b32 s53, v234, 41
	v_readlane_b32 s54, v234, 42
	v_readlane_b32 s55, v234, 43
	v_readlane_b32 s60, v234, 48
	v_readlane_b32 s61, v234, 49
	s_mov_b64 s[58:59], s[66:67]
	s_ashr_i32 s21, s20, 31
	v_and_b32_e32 v60, 0x7f, v40
	v_lshlrev_b32_e32 v36, 4, v60
	v_lshlrev_b32_e32 v59, 2, v60
	s_waitcnt vmcnt(0)
	v_add_f32_e32 v9, v9, v10
	global_load_dword v10, v8, s[22:23] offset:16
	s_nop 0
	global_load_dword v8, v8, s[56:57]
	v_readlane_b32 s52, v234, 24
	v_readlane_b32 s53, v234, 25
	v_readlane_b32 s54, v234, 26
	v_readlane_b32 s55, v234, 27
	v_readlane_b32 s56, v234, 28
	v_readlane_b32 s57, v234, 29
	v_readlane_b32 s58, v234, 30
	v_readlane_b32 s59, v234, 31
	v_readlane_b32 s60, v234, 32
	v_readlane_b32 s61, v234, 33
	v_readlane_b32 s62, v234, 34
	v_readlane_b32 s63, v234, 35
	v_readlane_b32 s64, v234, 36
	v_readlane_b32 s65, v234, 37
	s_mov_b64 s[52:53], s[56:57]
	s_lshl_b64 s[22:23], s[20:21], 2
	s_mov_b64 s[54:55], s[58:59]
	s_mov_b64 s[56:57], s[60:61]
	s_mov_b64 s[58:59], s[62:63]
	s_add_u32 s24, s58, s22
	s_addc_u32 s25, s59, s23
	v_readlane_b32 s66, v234, 38
	v_readlane_b32 s67, v234, 39
	s_mov_b64 s[60:61], s[64:65]
	s_waitcnt vmcnt(0)
	v_add_f32_e32 v10, v10, v8
	v_min_f32_e32 v26, 0, v10
	v_mul_f32_e64 v10, |v10|, s47
	v_exp_f32_e32 v27, v10
	v_mov_b32_e32 v8, 0
	v_add_f32_e32 v12, 1.0, v27
	v_add_f32_e32 v10, -1.0, v12
	v_sub_f32_e32 v11, v10, v12
	v_add_f32_e32 v11, 1.0, v11
	v_sub_f32_e32 v10, v27, v10
	v_add_f32_e32 v13, v10, v11
	v_frexp_mant_f32_e32 v10, v12
	v_cmp_gt_f32_e32 vcc, s48, v10
	v_cvt_f64_f32_e32 v[10:11], v12
	v_frexp_exp_i32_f64_e32 v10, v[10:11]
	v_subbrev_co_u32_e32 v18, vcc, 0, v10, vcc
	v_sub_u32_e32 v10, 0, v18
	v_ldexp_f32 v11, v12, v10
	v_add_f32_e32 v12, -1.0, v11
	v_add_f32_e32 v14, 1.0, v11
	v_ldexp_f32 v10, v13, v10
	v_add_f32_e32 v13, 1.0, v12
	v_add_f32_e32 v15, -1.0, v14
	v_sub_f32_e32 v13, v11, v13
	v_sub_f32_e32 v11, v11, v15
	v_add_f32_e32 v13, v10, v13
	v_add_f32_e32 v10, v10, v11
	v_add_f32_e32 v19, v14, v10
	v_rcp_f32_e32 v21, v19
	v_sub_f32_e32 v11, v19, v14
	v_sub_f32_e32 v20, v10, v11
	v_add_f32_e32 v11, v12, v13
	v_mul_f32_e32 v23, v11, v21
	v_sub_f32_e32 v10, v11, v12
	v_mul_f32_e32 v12, v19, v23
	v_fma_f32 v14, v23, v19, -v12
	v_fmac_f32_e32 v14, v23, v20
	v_sub_f32_e32 v22, v13, v10
	v_add_f32_e32 v10, v12, v14
	v_sub_f32_e32 v13, v11, v10
	v_pk_add_f32 v[16:17], v[10:11], v[12:13] neg_lo:[0,1] neg_hi:[0,1]
	v_mov_b32_e32 v15, v10
	v_pk_add_f32 v[10:11], v[16:17], v[14:15] neg_lo:[0,1] neg_hi:[0,1]
	v_cmp_neq_f32_e32 vcc, s50, v27
	v_add_f32_e32 v11, v22, v11
	v_add_f32_e32 v10, v10, v11
	v_add_f32_e32 v11, v13, v10
	v_mul_f32_e32 v22, v21, v11
	v_mul_f32_e32 v12, v19, v22
	v_fma_f32 v14, v22, v19, -v12
	v_fmac_f32_e32 v14, v22, v20
	v_sub_f32_e32 v13, v13, v11
	v_add_f32_e32 v19, v10, v13
	v_add_f32_e32 v10, v12, v14
	v_sub_f32_e32 v13, v11, v10
	v_pk_add_f32 v[16:17], v[10:11], v[12:13] neg_lo:[0,1] neg_hi:[0,1]
	v_mov_b32_e32 v15, v10
	v_pk_add_f32 v[10:11], v[16:17], v[14:15] neg_lo:[0,1] neg_hi:[0,1]
	s_nop 0
	v_add_f32_e32 v11, v19, v11
	v_add_f32_e32 v10, v10, v11
	v_add_f32_e32 v11, v23, v22
	v_add_f32_e32 v10, v13, v10
	v_sub_f32_e32 v12, v11, v23
	v_mul_f32_e32 v10, v21, v10
	v_sub_f32_e32 v12, v22, v12
	v_add_f32_e32 v12, v12, v10
	v_add_f32_e32 v14, v11, v12
	v_mul_f32_e32 v15, v14, v14
	v_fmamk_f32 v10, v15, 0x3e9b6dac, v62
	v_fmaak_f32 v39, v15, v10, 0x3f2aaada
	v_cvt_f32_i32_e32 v10, v18
	v_sub_f32_e32 v11, v14, v11
	v_sub_f32_e32 v11, v12, v11
	v_ldexp_f32 v16, v11, 1
	v_mul_f32_e32 v11, v14, v15
	v_ldexp_f32 v13, v14, 1
	v_pk_mul_f32 v[14:15], v[10:11], v[38:39]
	s_nop 0
	v_fma_f32 v12, v10, s49, -v14
	v_fmac_f32_e32 v12, 0xb102e308, v10
	v_pk_add_f32 v[10:11], v[14:15], v[12:13]
	s_nop 0
	v_sub_f32_e32 v13, v11, v13
	v_sub_f32_e32 v13, v15, v13
	v_add_f32_e32 v17, v16, v13
	v_mov_b32_e32 v16, v14
	v_pk_add_f32 v[14:15], v[10:11], v[14:15] neg_lo:[0,1] neg_hi:[0,1]
	v_pk_add_f32 v[18:19], v[10:11], v[16:17]
	v_mov_b32_e32 v13, v10
	v_mov_b32_e32 v15, v19
	v_pk_add_f32 v[20:21], v[12:13], v[14:15] neg_lo:[0,1] neg_hi:[0,1]
	v_pk_add_f32 v[12:13], v[12:13], v[14:15]
	v_mov_b32_e32 v24, v11
	v_pk_add_f32 v[14:15], v[12:13], v[10:11] op_sel:[1,0] op_sel_hi:[0,1] neg_lo:[0,1] neg_hi:[0,1]
	v_pk_add_f32 v[22:23], v[18:19], v[14:15] op_sel_hi:[1,0] neg_lo:[0,1] neg_hi:[0,1]
	v_mov_b32_e32 v18, v19
	v_mov_b32_e32 v19, v13
	v_mov_b32_e32 v25, v14
	v_pk_add_f32 v[14:15], v[18:19], v[24:25] neg_lo:[0,1] neg_hi:[0,1]
	v_mov_b32_e32 v16, v17
	v_mov_b32_e32 v17, v10
	v_pk_add_f32 v[10:11], v[16:17], v[14:15] neg_lo:[0,1] neg_hi:[0,1]
	v_mov_b32_e32 v22, v20
	v_pk_add_f32 v[14:15], v[22:23], v[10:11]
	v_mov_b32_e32 v21, v13
	v_pk_add_f32 v[16:17], v[14:15], v[14:15] op_sel:[0,1] op_sel_hi:[1,0]
	s_nop 0
	v_pk_add_f32 v[12:13], v[12:13], v[16:17] op_sel:[1,0] op_sel_hi:[0,1]
	v_mov_b32_e32 v15, v12
	v_pk_add_f32 v[18:19], v[14:15], v[20:21] neg_lo:[0,1] neg_hi:[0,1]
	v_mov_b32_e32 v11, v16
	v_sub_f32_e32 v13, v14, v18
	v_pk_add_f32 v[10:11], v[10:11], v[18:19] neg_lo:[0,1] neg_hi:[0,1]
	v_sub_f32_e32 v13, v20, v13
	v_add_f32_e32 v10, v10, v13
	v_add_f32_e32 v10, v10, v11
	global_load_dword v11, v37, s[24:25]
	v_add_f32_e32 v10, v12, v10
	v_cndmask_b32_e32 v10, v68, v10, vcc
	v_cmp_ngt_f32_e32 vcc, -1.0, v27
	s_lshl_b64 s[24:25], s[20:21], 19
	s_nop 0
	v_cndmask_b32_e32 v10, v69, v10, vcc
	v_cmp_neq_f32_e32 vcc, -1.0, v27
	s_nop 1
	v_cndmask_b32_e32 v10, v70, v10, vcc
	v_cmp_lt_f32_e64 vcc, |v27|, s51
	s_nop 1
	v_cndmask_b32_e32 v10, v10, v27, vcc
	v_sub_f32_e32 v10, v26, v10
	s_waitcnt vmcnt(0)
	v_add_f32_e32 v10, v11, v10
	v_max_f32_e32 v39, v10, v9
	v_sub_f32_e32 v9, v9, v39
	v_mul_f32_e32 v9, 0x3fb8aa3b, v9
	v_exp_f32_e32 v58, v9
	v_sub_f32_e32 v9, v10, v39
	v_mul_f32_e32 v9, 0x3fb8aa3b, v9
	v_ashrrev_i32_e32 v10, 7, v40
	v_exp_f32_e32 v42, v9
	v_add_u32_e32 v9, 0, v36
	v_ashrrev_i32_e32 v11, 31, v10
	ds_read_b128 v[12:15], v9 offset:2048
	v_lshlrev_b64 v[16:17], 11, v[10:11]
	v_lshl_add_u64 v[16:17], s[24:25], 0, v[16:17]
	v_lshl_add_u64 v[46:47], s[54:55], 0, v[16:17]
	v_readlane_b32 s52, v234, 0
	v_readlane_b32 s53, v234, 1
	v_mov_b32_e32 v44, v42
	v_mov_b32_e32 v45, v42
	v_lshl_add_u64 v[48:49], s[52:53], 0, v[16:17]
	v_lshl_add_u32 v61, v10, 2, 0
	s_mov_b32 s24, -8
	v_mov_b32_e32 v9, v8
	v_mov_b32_e32 v10, v8
	v_mov_b32_e32 v11, v8
	v_readlane_b32 s54, v234, 2
	v_readlane_b32 s55, v234, 3
	v_readlane_b32 s56, v46, 0
	v_readlane_b32 s57, v47, 0
	v_readlane_b32 s58, v48, 0
	v_readlane_b32 s59, v49, 0
	v_mov_b32_e32 v43, v42
	v_add_u32_e32 v71, 0x400, v61
	v_mov_b32_e32 v144, v36
	v_add_u32_e32 v145, 0x2000, v36
	v_add_u32_e32 v146, 0x4000, v36
	v_add_u32_e32 v147, 0x6000, v36
	v_add_u32_e32 v94, 0x8000, v36
	v_add_u32_e32 v95, 0xa000, v36
	v_add_u32_e32 v236, 0xc000, v36
	v_add_u32_e32 v237, 0xe000, v36
	s_add_u32 s58, s58, 0x50e2040
	s_addc_u32 s59, s59, 0
	global_load_dwordx4 v[96:99], v144, s[56:57] nt
	global_load_dwordx4 v[100:103], v145, s[56:57] nt
	global_load_dwordx4 v[104:107], v146, s[56:57] nt
	global_load_dwordx4 v[108:111], v147, s[56:57] nt
	global_load_dwordx4 v[112:115], v94, s[56:57] nt
	global_load_dwordx4 v[116:119], v95, s[56:57] nt
	global_load_dwordx4 v[120:123], v236, s[56:57] nt
	global_load_dwordx4 v[124:127], v237, s[56:57] nt
	s_add_u32 s56, s56, 0x10000
	s_addc_u32 s57, s57, 0
	global_load_dwordx4 v[72:75], v144, s[56:57] nt
	global_load_dwordx4 v[76:79], v145, s[56:57] nt
	global_load_dwordx4 v[80:83], v146, s[56:57] nt
	global_load_dwordx4 v[32:35], v147, s[56:57] nt
	global_load_dwordx4 v[28:31], v94, s[56:57] nt
	global_load_dwordx4 v[24:27], v95, s[56:57] nt
	global_load_dwordx4 v[20:23], v236, s[56:57] nt
	global_load_dwordx4 v[16:19], v237, s[56:57] nt
	s_add_u32 s56, s56, 0x10000
	s_addc_u32 s57, s57, 0
	ds_read2_b32 v[128:129], v61 offset0:0 offset1:4
	ds_read2_b32 v[130:131], v61 offset0:8 offset1:12
	ds_read2_b32 v[132:133], v61 offset0:16 offset1:20
	ds_read2_b32 v[134:135], v61 offset0:24 offset1:28
	ds_read2_b32 v[136:137], v71 offset0:0 offset1:4
	ds_read2_b32 v[138:139], v71 offset0:8 offset1:12
	ds_read2_b32 v[140:141], v71 offset0:16 offset1:20
	ds_read2_b32 v[142:143], v71 offset0:24 offset1:28
	s_waitcnt lgkmcnt(0)
	s_waitcnt vmcnt(15)
	v_mul_f32_e32 v50, v58, v136
	v_pk_fma_f32 v[8:9], v[96:97], v[128:129], v[8:9] op_sel_hi:[1,0,1]
	v_pk_fma_f32 v[10:11], v[98:99], v[128:129], v[10:11] op_sel_hi:[1,0,1]
	v_pk_mul_f32 v[84:85], v[12:13], v[50:51] op_sel_hi:[1,0]
	v_pk_mul_f32 v[86:87], v[14:15], v[50:51] op_sel_hi:[1,0]
	v_pk_fma_f32 v[96:97], v[44:45], v[96:97], v[84:85]
	v_pk_fma_f32 v[98:99], v[42:43], v[98:99], v[86:87]
	global_store_dwordx4 v144, v[96:99], s[58:59] nt
	s_waitcnt vmcnt(15)
	v_mul_f32_e32 v50, v58, v137
	v_pk_fma_f32 v[8:9], v[100:101], v[128:129], v[8:9] op_sel:[0,1,0] op_sel_hi:[1,1,1]
	v_pk_fma_f32 v[10:11], v[102:103], v[128:129], v[10:11] op_sel:[0,1,0] op_sel_hi:[1,1,1]
	v_pk_mul_f32 v[84:85], v[12:13], v[50:51] op_sel_hi:[1,0]
	v_pk_mul_f32 v[86:87], v[14:15], v[50:51] op_sel_hi:[1,0]
	v_pk_fma_f32 v[100:101], v[44:45], v[100:101], v[84:85]
	v_pk_fma_f32 v[102:103], v[42:43], v[102:103], v[86:87]
	global_store_dwordx4 v145, v[100:103], s[58:59] nt
	s_waitcnt vmcnt(15)
	v_mul_f32_e32 v50, v58, v138
	v_pk_fma_f32 v[8:9], v[104:105], v[130:131], v[8:9] op_sel_hi:[1,0,1]
	v_pk_fma_f32 v[10:11], v[106:107], v[130:131], v[10:11] op_sel_hi:[1,0,1]
	v_pk_mul_f32 v[84:85], v[12:13], v[50:51] op_sel_hi:[1,0]
	v_pk_mul_f32 v[86:87], v[14:15], v[50:51] op_sel_hi:[1,0]
	v_pk_fma_f32 v[104:105], v[44:45], v[104:105], v[84:85]
	v_pk_fma_f32 v[106:107], v[42:43], v[106:107], v[86:87]
	global_store_dwordx4 v146, v[104:107], s[58:59] nt
	s_waitcnt vmcnt(15)
	v_mul_f32_e32 v50, v58, v139
	v_pk_fma_f32 v[8:9], v[108:109], v[130:131], v[8:9] op_sel:[0,1,0] op_sel_hi:[1,1,1]
	v_pk_fma_f32 v[10:11], v[110:111], v[130:131], v[10:11] op_sel:[0,1,0] op_sel_hi:[1,1,1]
	v_pk_mul_f32 v[84:85], v[12:13], v[50:51] op_sel_hi:[1,0]
	v_pk_mul_f32 v[86:87], v[14:15], v[50:51] op_sel_hi:[1,0]
	v_pk_fma_f32 v[108:109], v[44:45], v[108:109], v[84:85]
	v_pk_fma_f32 v[110:111], v[42:43], v[110:111], v[86:87]
	global_store_dwordx4 v147, v[108:111], s[58:59] nt
	s_waitcnt vmcnt(15)
	v_mul_f32_e32 v50, v58, v140
	v_pk_fma_f32 v[8:9], v[112:113], v[132:133], v[8:9] op_sel_hi:[1,0,1]
	v_pk_fma_f32 v[10:11], v[114:115], v[132:133], v[10:11] op_sel_hi:[1,0,1]
	v_pk_mul_f32 v[84:85], v[12:13], v[50:51] op_sel_hi:[1,0]
	v_pk_mul_f32 v[86:87], v[14:15], v[50:51] op_sel_hi:[1,0]
	v_pk_fma_f32 v[112:113], v[44:45], v[112:113], v[84:85]
	v_pk_fma_f32 v[114:115], v[42:43], v[114:115], v[86:87]
	global_store_dwordx4 v94, v[112:115], s[58:59] nt
	s_waitcnt vmcnt(15)
	v_mul_f32_e32 v50, v58, v141
	v_pk_fma_f32 v[8:9], v[116:117], v[132:133], v[8:9] op_sel:[0,1,0] op_sel_hi:[1,1,1]
	v_pk_fma_f32 v[10:11], v[118:119], v[132:133], v[10:11] op_sel:[0,1,0] op_sel_hi:[1,1,1]
	v_pk_mul_f32 v[84:85], v[12:13], v[50:51] op_sel_hi:[1,0]
	v_pk_mul_f32 v[86:87], v[14:15], v[50:51] op_sel_hi:[1,0]
	v_pk_fma_f32 v[116:117], v[44:45], v[116:117], v[84:85]
	v_pk_fma_f32 v[118:119], v[42:43], v[118:119], v[86:87]
	global_store_dwordx4 v95, v[116:119], s[58:59] nt
	s_waitcnt vmcnt(15)
	v_mul_f32_e32 v50, v58, v142
	v_pk_fma_f32 v[8:9], v[120:121], v[134:135], v[8:9] op_sel_hi:[1,0,1]
	v_pk_fma_f32 v[10:11], v[122:123], v[134:135], v[10:11] op_sel_hi:[1,0,1]
	v_pk_mul_f32 v[84:85], v[12:13], v[50:51] op_sel_hi:[1,0]
	v_pk_mul_f32 v[86:87], v[14:15], v[50:51] op_sel_hi:[1,0]
	v_pk_fma_f32 v[120:121], v[44:45], v[120:121], v[84:85]
	v_pk_fma_f32 v[122:123], v[42:43], v[122:123], v[86:87]
	global_store_dwordx4 v236, v[120:123], s[58:59] nt
	s_waitcnt vmcnt(15)
	v_mul_f32_e32 v50, v58, v143
	v_pk_fma_f32 v[8:9], v[124:125], v[134:135], v[8:9] op_sel:[0,1,0] op_sel_hi:[1,1,1]
	v_pk_fma_f32 v[10:11], v[126:127], v[134:135], v[10:11] op_sel:[0,1,0] op_sel_hi:[1,1,1]
	v_pk_mul_f32 v[84:85], v[12:13], v[50:51] op_sel_hi:[1,0]
	v_pk_mul_f32 v[86:87], v[14:15], v[50:51] op_sel_hi:[1,0]
	v_pk_fma_f32 v[124:125], v[44:45], v[124:125], v[84:85]
	v_pk_fma_f32 v[126:127], v[42:43], v[126:127], v[86:87]
	global_store_dwordx4 v237, v[124:127], s[58:59] nt
	s_add_u32 s58, s58, 0x10000
	s_addc_u32 s59, s59, 0
	global_load_dwordx4 v[96:99], v144, s[56:57] nt
	global_load_dwordx4 v[100:103], v145, s[56:57] nt
	global_load_dwordx4 v[104:107], v146, s[56:57] nt
	global_load_dwordx4 v[108:111], v147, s[56:57] nt
	global_load_dwordx4 v[112:115], v94, s[56:57] nt
	global_load_dwordx4 v[116:119], v95, s[56:57] nt
	global_load_dwordx4 v[120:123], v236, s[56:57] nt
	global_load_dwordx4 v[124:127], v237, s[56:57] nt
	s_add_u32 s56, s56, 0x10000
	s_addc_u32 s57, s57, 0
	ds_read2_b32 v[128:129], v61 offset0:32 offset1:36
	ds_read2_b32 v[130:131], v61 offset0:40 offset1:44
	ds_read2_b32 v[132:133], v61 offset0:48 offset1:52
	ds_read2_b32 v[134:135], v61 offset0:56 offset1:60
	ds_read2_b32 v[136:137], v71 offset0:32 offset1:36
	ds_read2_b32 v[138:139], v71 offset0:40 offset1:44
	ds_read2_b32 v[140:141], v71 offset0:48 offset1:52
	ds_read2_b32 v[142:143], v71 offset0:56 offset1:60
	s_waitcnt lgkmcnt(0)
	s_waitcnt vmcnt(23)
	v_mul_f32_e32 v50, v58, v136
	v_pk_fma_f32 v[8:9], v[72:73], v[128:129], v[8:9] op_sel_hi:[1,0,1]
	v_pk_fma_f32 v[10:11], v[74:75], v[128:129], v[10:11] op_sel_hi:[1,0,1]
	v_pk_mul_f32 v[84:85], v[12:13], v[50:51] op_sel_hi:[1,0]
	v_pk_mul_f32 v[86:87], v[14:15], v[50:51] op_sel_hi:[1,0]
	v_pk_fma_f32 v[72:73], v[44:45], v[72:73], v[84:85]
	v_pk_fma_f32 v[74:75], v[42:43], v[74:75], v[86:87]
	global_store_dwordx4 v144, v[72:75], s[58:59] nt
	s_waitcnt vmcnt(23)
	v_mul_f32_e32 v50, v58, v137
	v_pk_fma_f32 v[8:9], v[76:77], v[128:129], v[8:9] op_sel:[0,1,0] op_sel_hi:[1,1,1]
	v_pk_fma_f32 v[10:11], v[78:79], v[128:129], v[10:11] op_sel:[0,1,0] op_sel_hi:[1,1,1]
	v_pk_mul_f32 v[84:85], v[12:13], v[50:51] op_sel_hi:[1,0]
	v_pk_mul_f32 v[86:87], v[14:15], v[50:51] op_sel_hi:[1,0]
	v_pk_fma_f32 v[76:77], v[44:45], v[76:77], v[84:85]
	v_pk_fma_f32 v[78:79], v[42:43], v[78:79], v[86:87]
	global_store_dwordx4 v145, v[76:79], s[58:59] nt
	s_waitcnt vmcnt(23)
	v_mul_f32_e32 v50, v58, v138
	v_pk_fma_f32 v[8:9], v[80:81], v[130:131], v[8:9] op_sel_hi:[1,0,1]
	v_pk_fma_f32 v[10:11], v[82:83], v[130:131], v[10:11] op_sel_hi:[1,0,1]
	v_pk_mul_f32 v[84:85], v[12:13], v[50:51] op_sel_hi:[1,0]
	v_pk_mul_f32 v[86:87], v[14:15], v[50:51] op_sel_hi:[1,0]
	v_pk_fma_f32 v[80:81], v[44:45], v[80:81], v[84:85]
	v_pk_fma_f32 v[82:83], v[42:43], v[82:83], v[86:87]
	global_store_dwordx4 v146, v[80:83], s[58:59] nt
	s_waitcnt vmcnt(23)
	v_mul_f32_e32 v50, v58, v139
	v_pk_fma_f32 v[8:9], v[32:33], v[130:131], v[8:9] op_sel:[0,1,0] op_sel_hi:[1,1,1]
	v_pk_fma_f32 v[10:11], v[34:35], v[130:131], v[10:11] op_sel:[0,1,0] op_sel_hi:[1,1,1]
	v_pk_mul_f32 v[84:85], v[12:13], v[50:51] op_sel_hi:[1,0]
	v_pk_mul_f32 v[86:87], v[14:15], v[50:51] op_sel_hi:[1,0]
	v_pk_fma_f32 v[32:33], v[44:45], v[32:33], v[84:85]
	v_pk_fma_f32 v[34:35], v[42:43], v[34:35], v[86:87]
	global_store_dwordx4 v147, v[32:35], s[58:59] nt
	s_waitcnt vmcnt(23)
	v_mul_f32_e32 v50, v58, v140
	v_pk_fma_f32 v[8:9], v[28:29], v[132:133], v[8:9] op_sel_hi:[1,0,1]
	v_pk_fma_f32 v[10:11], v[30:31], v[132:133], v[10:11] op_sel_hi:[1,0,1]
	v_pk_mul_f32 v[84:85], v[12:13], v[50:51] op_sel_hi:[1,0]
	v_pk_mul_f32 v[86:87], v[14:15], v[50:51] op_sel_hi:[1,0]
	v_pk_fma_f32 v[28:29], v[44:45], v[28:29], v[84:85]
	v_pk_fma_f32 v[30:31], v[42:43], v[30:31], v[86:87]
	global_store_dwordx4 v94, v[28:31], s[58:59] nt
	s_waitcnt vmcnt(23)
	v_mul_f32_e32 v50, v58, v141
	v_pk_fma_f32 v[8:9], v[24:25], v[132:133], v[8:9] op_sel:[0,1,0] op_sel_hi:[1,1,1]
	v_pk_fma_f32 v[10:11], v[26:27], v[132:133], v[10:11] op_sel:[0,1,0] op_sel_hi:[1,1,1]
	v_pk_mul_f32 v[84:85], v[12:13], v[50:51] op_sel_hi:[1,0]
	v_pk_mul_f32 v[86:87], v[14:15], v[50:51] op_sel_hi:[1,0]
	v_pk_fma_f32 v[24:25], v[44:45], v[24:25], v[84:85]
	v_pk_fma_f32 v[26:27], v[42:43], v[26:27], v[86:87]
	global_store_dwordx4 v95, v[24:27], s[58:59] nt
	s_waitcnt vmcnt(23)
	v_mul_f32_e32 v50, v58, v142
	v_pk_fma_f32 v[8:9], v[20:21], v[134:135], v[8:9] op_sel_hi:[1,0,1]
	v_pk_fma_f32 v[10:11], v[22:23], v[134:135], v[10:11] op_sel_hi:[1,0,1]
	v_pk_mul_f32 v[84:85], v[12:13], v[50:51] op_sel_hi:[1,0]
	v_pk_mul_f32 v[86:87], v[14:15], v[50:51] op_sel_hi:[1,0]
	v_pk_fma_f32 v[20:21], v[44:45], v[20:21], v[84:85]
	v_pk_fma_f32 v[22:23], v[42:43], v[22:23], v[86:87]
	global_store_dwordx4 v236, v[20:23], s[58:59] nt
	s_waitcnt vmcnt(23)
	v_mul_f32_e32 v50, v58, v143
	v_pk_fma_f32 v[8:9], v[16:17], v[134:135], v[8:9] op_sel:[0,1,0] op_sel_hi:[1,1,1]
	v_pk_fma_f32 v[10:11], v[18:19], v[134:135], v[10:11] op_sel:[0,1,0] op_sel_hi:[1,1,1]
	v_pk_mul_f32 v[84:85], v[12:13], v[50:51] op_sel_hi:[1,0]
	v_pk_mul_f32 v[86:87], v[14:15], v[50:51] op_sel_hi:[1,0]
	v_pk_fma_f32 v[16:17], v[44:45], v[16:17], v[84:85]
	v_pk_fma_f32 v[18:19], v[42:43], v[18:19], v[86:87]
	global_store_dwordx4 v237, v[16:19], s[58:59] nt
	s_add_u32 s58, s58, 0x10000
	s_addc_u32 s59, s59, 0
	global_load_dwordx4 v[72:75], v144, s[56:57] nt
	global_load_dwordx4 v[76:79], v145, s[56:57] nt
	global_load_dwordx4 v[80:83], v146, s[56:57] nt
	global_load_dwordx4 v[32:35], v147, s[56:57] nt
	global_load_dwordx4 v[28:31], v94, s[56:57] nt
	global_load_dwordx4 v[24:27], v95, s[56:57] nt
	global_load_dwordx4 v[20:23], v236, s[56:57] nt
	global_load_dwordx4 v[16:19], v237, s[56:57] nt
	s_add_u32 s56, s56, 0x10000
	s_addc_u32 s57, s57, 0
	ds_read2_b32 v[128:129], v61 offset0:64 offset1:68
	ds_read2_b32 v[130:131], v61 offset0:72 offset1:76
	ds_read2_b32 v[132:133], v61 offset0:80 offset1:84
	ds_read2_b32 v[134:135], v61 offset0:88 offset1:92
	ds_read2_b32 v[136:137], v71 offset0:64 offset1:68
	ds_read2_b32 v[138:139], v71 offset0:72 offset1:76
	ds_read2_b32 v[140:141], v71 offset0:80 offset1:84
	ds_read2_b32 v[142:143], v71 offset0:88 offset1:92
	s_waitcnt lgkmcnt(0)
	s_waitcnt vmcnt(23)
	v_mul_f32_e32 v50, v58, v136
	v_pk_fma_f32 v[8:9], v[96:97], v[128:129], v[8:9] op_sel_hi:[1,0,1]
	v_pk_fma_f32 v[10:11], v[98:99], v[128:129], v[10:11] op_sel_hi:[1,0,1]
	v_pk_mul_f32 v[84:85], v[12:13], v[50:51] op_sel_hi:[1,0]
	v_pk_mul_f32 v[86:87], v[14:15], v[50:51] op_sel_hi:[1,0]
	v_pk_fma_f32 v[96:97], v[44:45], v[96:97], v[84:85]
	v_pk_fma_f32 v[98:99], v[42:43], v[98:99], v[86:87]
	global_store_dwordx4 v144, v[96:99], s[58:59] nt
	s_waitcnt vmcnt(23)
	v_mul_f32_e32 v50, v58, v137
	v_pk_fma_f32 v[8:9], v[100:101], v[128:129], v[8:9] op_sel:[0,1,0] op_sel_hi:[1,1,1]
	v_pk_fma_f32 v[10:11], v[102:103], v[128:129], v[10:11] op_sel:[0,1,0] op_sel_hi:[1,1,1]
	v_pk_mul_f32 v[84:85], v[12:13], v[50:51] op_sel_hi:[1,0]
	v_pk_mul_f32 v[86:87], v[14:15], v[50:51] op_sel_hi:[1,0]
	v_pk_fma_f32 v[100:101], v[44:45], v[100:101], v[84:85]
	v_pk_fma_f32 v[102:103], v[42:43], v[102:103], v[86:87]
	global_store_dwordx4 v145, v[100:103], s[58:59] nt
	s_waitcnt vmcnt(23)
	v_mul_f32_e32 v50, v58, v138
	v_pk_fma_f32 v[8:9], v[104:105], v[130:131], v[8:9] op_sel_hi:[1,0,1]
	v_pk_fma_f32 v[10:11], v[106:107], v[130:131], v[10:11] op_sel_hi:[1,0,1]
	v_pk_mul_f32 v[84:85], v[12:13], v[50:51] op_sel_hi:[1,0]
	v_pk_mul_f32 v[86:87], v[14:15], v[50:51] op_sel_hi:[1,0]
	v_pk_fma_f32 v[104:105], v[44:45], v[104:105], v[84:85]
	v_pk_fma_f32 v[106:107], v[42:43], v[106:107], v[86:87]
	global_store_dwordx4 v146, v[104:107], s[58:59] nt
	s_waitcnt vmcnt(23)
	v_mul_f32_e32 v50, v58, v139
	v_pk_fma_f32 v[8:9], v[108:109], v[130:131], v[8:9] op_sel:[0,1,0] op_sel_hi:[1,1,1]
	v_pk_fma_f32 v[10:11], v[110:111], v[130:131], v[10:11] op_sel:[0,1,0] op_sel_hi:[1,1,1]
	v_pk_mul_f32 v[84:85], v[12:13], v[50:51] op_sel_hi:[1,0]
	v_pk_mul_f32 v[86:87], v[14:15], v[50:51] op_sel_hi:[1,0]
	v_pk_fma_f32 v[108:109], v[44:45], v[108:109], v[84:85]
	v_pk_fma_f32 v[110:111], v[42:43], v[110:111], v[86:87]
	global_store_dwordx4 v147, v[108:111], s[58:59] nt
	s_waitcnt vmcnt(23)
	v_mul_f32_e32 v50, v58, v140
	v_pk_fma_f32 v[8:9], v[112:113], v[132:133], v[8:9] op_sel_hi:[1,0,1]
	v_pk_fma_f32 v[10:11], v[114:115], v[132:133], v[10:11] op_sel_hi:[1,0,1]
	v_pk_mul_f32 v[84:85], v[12:13], v[50:51] op_sel_hi:[1,0]
	v_pk_mul_f32 v[86:87], v[14:15], v[50:51] op_sel_hi:[1,0]
	v_pk_fma_f32 v[112:113], v[44:45], v[112:113], v[84:85]
	v_pk_fma_f32 v[114:115], v[42:43], v[114:115], v[86:87]
	global_store_dwordx4 v94, v[112:115], s[58:59] nt
	s_waitcnt vmcnt(23)
	v_mul_f32_e32 v50, v58, v141
	v_pk_fma_f32 v[8:9], v[116:117], v[132:133], v[8:9] op_sel:[0,1,0] op_sel_hi:[1,1,1]
	v_pk_fma_f32 v[10:11], v[118:119], v[132:133], v[10:11] op_sel:[0,1,0] op_sel_hi:[1,1,1]
	v_pk_mul_f32 v[84:85], v[12:13], v[50:51] op_sel_hi:[1,0]
	v_pk_mul_f32 v[86:87], v[14:15], v[50:51] op_sel_hi:[1,0]
	v_pk_fma_f32 v[116:117], v[44:45], v[116:117], v[84:85]
	v_pk_fma_f32 v[118:119], v[42:43], v[118:119], v[86:87]
	global_store_dwordx4 v95, v[116:119], s[58:59] nt
	s_waitcnt vmcnt(23)
	v_mul_f32_e32 v50, v58, v142
	v_pk_fma_f32 v[8:9], v[120:121], v[134:135], v[8:9] op_sel_hi:[1,0,1]
	v_pk_fma_f32 v[10:11], v[122:123], v[134:135], v[10:11] op_sel_hi:[1,0,1]
	v_pk_mul_f32 v[84:85], v[12:13], v[50:51] op_sel_hi:[1,0]
	v_pk_mul_f32 v[86:87], v[14:15], v[50:51] op_sel_hi:[1,0]
	v_pk_fma_f32 v[120:121], v[44:45], v[120:121], v[84:85]
	v_pk_fma_f32 v[122:123], v[42:43], v[122:123], v[86:87]
	global_store_dwordx4 v236, v[120:123], s[58:59] nt
	s_waitcnt vmcnt(23)
	v_mul_f32_e32 v50, v58, v143
	v_pk_fma_f32 v[8:9], v[124:125], v[134:135], v[8:9] op_sel:[0,1,0] op_sel_hi:[1,1,1]
	v_pk_fma_f32 v[10:11], v[126:127], v[134:135], v[10:11] op_sel:[0,1,0] op_sel_hi:[1,1,1]
	v_pk_mul_f32 v[84:85], v[12:13], v[50:51] op_sel_hi:[1,0]
	v_pk_mul_f32 v[86:87], v[14:15], v[50:51] op_sel_hi:[1,0]
	v_pk_fma_f32 v[124:125], v[44:45], v[124:125], v[84:85]
	v_pk_fma_f32 v[126:127], v[42:43], v[126:127], v[86:87]
	global_store_dwordx4 v237, v[124:127], s[58:59] nt
	s_add_u32 s58, s58, 0x10000
	s_addc_u32 s59, s59, 0
	global_load_dwordx4 v[96:99], v144, s[56:57] nt
	global_load_dwordx4 v[100:103], v145, s[56:57] nt
	global_load_dwordx4 v[104:107], v146, s[56:57] nt
	global_load_dwordx4 v[108:111], v147, s[56:57] nt
	global_load_dwordx4 v[112:115], v94, s[56:57] nt
	global_load_dwordx4 v[116:119], v95, s[56:57] nt
	global_load_dwordx4 v[120:123], v236, s[56:57] nt
	global_load_dwordx4 v[124:127], v237, s[56:57] nt
	s_add_u32 s56, s56, 0x10000
	s_addc_u32 s57, s57, 0
	ds_read2_b32 v[128:129], v61 offset0:96 offset1:100
	ds_read2_b32 v[130:131], v61 offset0:104 offset1:108
	ds_read2_b32 v[132:133], v61 offset0:112 offset1:116
	ds_read2_b32 v[134:135], v61 offset0:120 offset1:124
	ds_read2_b32 v[136:137], v71 offset0:96 offset1:100
	ds_read2_b32 v[138:139], v71 offset0:104 offset1:108
	ds_read2_b32 v[140:141], v71 offset0:112 offset1:116
	ds_read2_b32 v[142:143], v71 offset0:120 offset1:124
	s_waitcnt lgkmcnt(0)
	s_waitcnt vmcnt(23)
	v_mul_f32_e32 v50, v58, v136
	v_pk_fma_f32 v[8:9], v[72:73], v[128:129], v[8:9] op_sel_hi:[1,0,1]
	v_pk_fma_f32 v[10:11], v[74:75], v[128:129], v[10:11] op_sel_hi:[1,0,1]
	v_pk_mul_f32 v[84:85], v[12:13], v[50:51] op_sel_hi:[1,0]
	v_pk_mul_f32 v[86:87], v[14:15], v[50:51] op_sel_hi:[1,0]
	v_pk_fma_f32 v[72:73], v[44:45], v[72:73], v[84:85]
	v_pk_fma_f32 v[74:75], v[42:43], v[74:75], v[86:87]
	global_store_dwordx4 v144, v[72:75], s[58:59] nt
	s_waitcnt vmcnt(23)
	v_mul_f32_e32 v50, v58, v137
	v_pk_fma_f32 v[8:9], v[76:77], v[128:129], v[8:9] op_sel:[0,1,0] op_sel_hi:[1,1,1]
	v_pk_fma_f32 v[10:11], v[78:79], v[128:129], v[10:11] op_sel:[0,1,0] op_sel_hi:[1,1,1]
	v_pk_mul_f32 v[84:85], v[12:13], v[50:51] op_sel_hi:[1,0]
	v_pk_mul_f32 v[86:87], v[14:15], v[50:51] op_sel_hi:[1,0]
	v_pk_fma_f32 v[76:77], v[44:45], v[76:77], v[84:85]
	v_pk_fma_f32 v[78:79], v[42:43], v[78:79], v[86:87]
	global_store_dwordx4 v145, v[76:79], s[58:59] nt
	s_waitcnt vmcnt(23)
	v_mul_f32_e32 v50, v58, v138
	v_pk_fma_f32 v[8:9], v[80:81], v[130:131], v[8:9] op_sel_hi:[1,0,1]
	v_pk_fma_f32 v[10:11], v[82:83], v[130:131], v[10:11] op_sel_hi:[1,0,1]
	v_pk_mul_f32 v[84:85], v[12:13], v[50:51] op_sel_hi:[1,0]
	v_pk_mul_f32 v[86:87], v[14:15], v[50:51] op_sel_hi:[1,0]
	v_pk_fma_f32 v[80:81], v[44:45], v[80:81], v[84:85]
	v_pk_fma_f32 v[82:83], v[42:43], v[82:83], v[86:87]
	global_store_dwordx4 v146, v[80:83], s[58:59] nt
	s_waitcnt vmcnt(23)
	v_mul_f32_e32 v50, v58, v139
	v_pk_fma_f32 v[8:9], v[32:33], v[130:131], v[8:9] op_sel:[0,1,0] op_sel_hi:[1,1,1]
	v_pk_fma_f32 v[10:11], v[34:35], v[130:131], v[10:11] op_sel:[0,1,0] op_sel_hi:[1,1,1]
	v_pk_mul_f32 v[84:85], v[12:13], v[50:51] op_sel_hi:[1,0]
	v_pk_mul_f32 v[86:87], v[14:15], v[50:51] op_sel_hi:[1,0]
	v_pk_fma_f32 v[32:33], v[44:45], v[32:33], v[84:85]
	v_pk_fma_f32 v[34:35], v[42:43], v[34:35], v[86:87]
	global_store_dwordx4 v147, v[32:35], s[58:59] nt
	s_waitcnt vmcnt(23)
	v_mul_f32_e32 v50, v58, v140
	v_pk_fma_f32 v[8:9], v[28:29], v[132:133], v[8:9] op_sel_hi:[1,0,1]
	v_pk_fma_f32 v[10:11], v[30:31], v[132:133], v[10:11] op_sel_hi:[1,0,1]
	v_pk_mul_f32 v[84:85], v[12:13], v[50:51] op_sel_hi:[1,0]
	v_pk_mul_f32 v[86:87], v[14:15], v[50:51] op_sel_hi:[1,0]
	v_pk_fma_f32 v[28:29], v[44:45], v[28:29], v[84:85]
	v_pk_fma_f32 v[30:31], v[42:43], v[30:31], v[86:87]
	global_store_dwordx4 v94, v[28:31], s[58:59] nt
	s_waitcnt vmcnt(23)
	v_mul_f32_e32 v50, v58, v141
	v_pk_fma_f32 v[8:9], v[24:25], v[132:133], v[8:9] op_sel:[0,1,0] op_sel_hi:[1,1,1]
	v_pk_fma_f32 v[10:11], v[26:27], v[132:133], v[10:11] op_sel:[0,1,0] op_sel_hi:[1,1,1]
	v_pk_mul_f32 v[84:85], v[12:13], v[50:51] op_sel_hi:[1,0]
	v_pk_mul_f32 v[86:87], v[14:15], v[50:51] op_sel_hi:[1,0]
	v_pk_fma_f32 v[24:25], v[44:45], v[24:25], v[84:85]
	v_pk_fma_f32 v[26:27], v[42:43], v[26:27], v[86:87]
	global_store_dwordx4 v95, v[24:27], s[58:59] nt
	s_waitcnt vmcnt(23)
	v_mul_f32_e32 v50, v58, v142
	v_pk_fma_f32 v[8:9], v[20:21], v[134:135], v[8:9] op_sel_hi:[1,0,1]
	v_pk_fma_f32 v[10:11], v[22:23], v[134:135], v[10:11] op_sel_hi:[1,0,1]
	v_pk_mul_f32 v[84:85], v[12:13], v[50:51] op_sel_hi:[1,0]
	v_pk_mul_f32 v[86:87], v[14:15], v[50:51] op_sel_hi:[1,0]
	v_pk_fma_f32 v[20:21], v[44:45], v[20:21], v[84:85]
	v_pk_fma_f32 v[22:23], v[42:43], v[22:23], v[86:87]
	global_store_dwordx4 v236, v[20:23], s[58:59] nt
	s_waitcnt vmcnt(23)
	v_mul_f32_e32 v50, v58, v143
	v_pk_fma_f32 v[8:9], v[16:17], v[134:135], v[8:9] op_sel:[0,1,0] op_sel_hi:[1,1,1]
	v_pk_fma_f32 v[10:11], v[18:19], v[134:135], v[10:11] op_sel:[0,1,0] op_sel_hi:[1,1,1]
	v_pk_mul_f32 v[84:85], v[12:13], v[50:51] op_sel_hi:[1,0]
	v_pk_mul_f32 v[86:87], v[14:15], v[50:51] op_sel_hi:[1,0]
	v_pk_fma_f32 v[16:17], v[44:45], v[16:17], v[84:85]
	v_pk_fma_f32 v[18:19], v[42:43], v[18:19], v[86:87]
	global_store_dwordx4 v237, v[16:19], s[58:59] nt
	s_add_u32 s58, s58, 0x10000
	s_addc_u32 s59, s59, 0
	global_load_dwordx4 v[72:75], v144, s[56:57] nt
	global_load_dwordx4 v[76:79], v145, s[56:57] nt
	global_load_dwordx4 v[80:83], v146, s[56:57] nt
	global_load_dwordx4 v[32:35], v147, s[56:57] nt
	global_load_dwordx4 v[28:31], v94, s[56:57] nt
	global_load_dwordx4 v[24:27], v95, s[56:57] nt
	global_load_dwordx4 v[20:23], v236, s[56:57] nt
	global_load_dwordx4 v[16:19], v237, s[56:57] nt
	s_add_u32 s56, s56, 0x10000
	s_addc_u32 s57, s57, 0
	ds_read2_b32 v[128:129], v61 offset0:128 offset1:132
	ds_read2_b32 v[130:131], v61 offset0:136 offset1:140
	ds_read2_b32 v[132:133], v61 offset0:144 offset1:148
	ds_read2_b32 v[134:135], v61 offset0:152 offset1:156
	ds_read2_b32 v[136:137], v71 offset0:128 offset1:132
	ds_read2_b32 v[138:139], v71 offset0:136 offset1:140
	ds_read2_b32 v[140:141], v71 offset0:144 offset1:148
	ds_read2_b32 v[142:143], v71 offset0:152 offset1:156
	s_waitcnt lgkmcnt(0)
	s_waitcnt vmcnt(23)
	v_mul_f32_e32 v50, v58, v136
	v_pk_fma_f32 v[8:9], v[96:97], v[128:129], v[8:9] op_sel_hi:[1,0,1]
	v_pk_fma_f32 v[10:11], v[98:99], v[128:129], v[10:11] op_sel_hi:[1,0,1]
	v_pk_mul_f32 v[84:85], v[12:13], v[50:51] op_sel_hi:[1,0]
	v_pk_mul_f32 v[86:87], v[14:15], v[50:51] op_sel_hi:[1,0]
	v_pk_fma_f32 v[96:97], v[44:45], v[96:97], v[84:85]
	v_pk_fma_f32 v[98:99], v[42:43], v[98:99], v[86:87]
	global_store_dwordx4 v144, v[96:99], s[58:59] nt
	s_waitcnt vmcnt(23)
	v_mul_f32_e32 v50, v58, v137
	v_pk_fma_f32 v[8:9], v[100:101], v[128:129], v[8:9] op_sel:[0,1,0] op_sel_hi:[1,1,1]
	v_pk_fma_f32 v[10:11], v[102:103], v[128:129], v[10:11] op_sel:[0,1,0] op_sel_hi:[1,1,1]
	v_pk_mul_f32 v[84:85], v[12:13], v[50:51] op_sel_hi:[1,0]
	v_pk_mul_f32 v[86:87], v[14:15], v[50:51] op_sel_hi:[1,0]
	v_pk_fma_f32 v[100:101], v[44:45], v[100:101], v[84:85]
	v_pk_fma_f32 v[102:103], v[42:43], v[102:103], v[86:87]
	global_store_dwordx4 v145, v[100:103], s[58:59] nt
	s_waitcnt vmcnt(23)
	v_mul_f32_e32 v50, v58, v138
	v_pk_fma_f32 v[8:9], v[104:105], v[130:131], v[8:9] op_sel_hi:[1,0,1]
	v_pk_fma_f32 v[10:11], v[106:107], v[130:131], v[10:11] op_sel_hi:[1,0,1]
	v_pk_mul_f32 v[84:85], v[12:13], v[50:51] op_sel_hi:[1,0]
	v_pk_mul_f32 v[86:87], v[14:15], v[50:51] op_sel_hi:[1,0]
	v_pk_fma_f32 v[104:105], v[44:45], v[104:105], v[84:85]
	v_pk_fma_f32 v[106:107], v[42:43], v[106:107], v[86:87]
	global_store_dwordx4 v146, v[104:107], s[58:59] nt
	s_waitcnt vmcnt(23)
	v_mul_f32_e32 v50, v58, v139
	v_pk_fma_f32 v[8:9], v[108:109], v[130:131], v[8:9] op_sel:[0,1,0] op_sel_hi:[1,1,1]
	v_pk_fma_f32 v[10:11], v[110:111], v[130:131], v[10:11] op_sel:[0,1,0] op_sel_hi:[1,1,1]
	v_pk_mul_f32 v[84:85], v[12:13], v[50:51] op_sel_hi:[1,0]
	v_pk_mul_f32 v[86:87], v[14:15], v[50:51] op_sel_hi:[1,0]
	v_pk_fma_f32 v[108:109], v[44:45], v[108:109], v[84:85]
	v_pk_fma_f32 v[110:111], v[42:43], v[110:111], v[86:87]
	global_store_dwordx4 v147, v[108:111], s[58:59] nt
	s_waitcnt vmcnt(23)
	v_mul_f32_e32 v50, v58, v140
	v_pk_fma_f32 v[8:9], v[112:113], v[132:133], v[8:9] op_sel_hi:[1,0,1]
	v_pk_fma_f32 v[10:11], v[114:115], v[132:133], v[10:11] op_sel_hi:[1,0,1]
	v_pk_mul_f32 v[84:85], v[12:13], v[50:51] op_sel_hi:[1,0]
	v_pk_mul_f32 v[86:87], v[14:15], v[50:51] op_sel_hi:[1,0]
	v_pk_fma_f32 v[112:113], v[44:45], v[112:113], v[84:85]
	v_pk_fma_f32 v[114:115], v[42:43], v[114:115], v[86:87]
	global_store_dwordx4 v94, v[112:115], s[58:59] nt
	s_waitcnt vmcnt(23)
	v_mul_f32_e32 v50, v58, v141
	v_pk_fma_f32 v[8:9], v[116:117], v[132:133], v[8:9] op_sel:[0,1,0] op_sel_hi:[1,1,1]
	v_pk_fma_f32 v[10:11], v[118:119], v[132:133], v[10:11] op_sel:[0,1,0] op_sel_hi:[1,1,1]
	v_pk_mul_f32 v[84:85], v[12:13], v[50:51] op_sel_hi:[1,0]
	v_pk_mul_f32 v[86:87], v[14:15], v[50:51] op_sel_hi:[1,0]
	v_pk_fma_f32 v[116:117], v[44:45], v[116:117], v[84:85]
	v_pk_fma_f32 v[118:119], v[42:43], v[118:119], v[86:87]
	global_store_dwordx4 v95, v[116:119], s[58:59] nt
	s_waitcnt vmcnt(23)
	v_mul_f32_e32 v50, v58, v142
	v_pk_fma_f32 v[8:9], v[120:121], v[134:135], v[8:9] op_sel_hi:[1,0,1]
	v_pk_fma_f32 v[10:11], v[122:123], v[134:135], v[10:11] op_sel_hi:[1,0,1]
	v_pk_mul_f32 v[84:85], v[12:13], v[50:51] op_sel_hi:[1,0]
	v_pk_mul_f32 v[86:87], v[14:15], v[50:51] op_sel_hi:[1,0]
	v_pk_fma_f32 v[120:121], v[44:45], v[120:121], v[84:85]
	v_pk_fma_f32 v[122:123], v[42:43], v[122:123], v[86:87]
	global_store_dwordx4 v236, v[120:123], s[58:59] nt
	s_waitcnt vmcnt(23)
	v_mul_f32_e32 v50, v58, v143
	v_pk_fma_f32 v[8:9], v[124:125], v[134:135], v[8:9] op_sel:[0,1,0] op_sel_hi:[1,1,1]
	v_pk_fma_f32 v[10:11], v[126:127], v[134:135], v[10:11] op_sel:[0,1,0] op_sel_hi:[1,1,1]
	v_pk_mul_f32 v[84:85], v[12:13], v[50:51] op_sel_hi:[1,0]
	v_pk_mul_f32 v[86:87], v[14:15], v[50:51] op_sel_hi:[1,0]
	v_pk_fma_f32 v[124:125], v[44:45], v[124:125], v[84:85]
	v_pk_fma_f32 v[126:127], v[42:43], v[126:127], v[86:87]
	global_store_dwordx4 v237, v[124:127], s[58:59] nt
	s_add_u32 s58, s58, 0x10000
	s_addc_u32 s59, s59, 0
	global_load_dwordx4 v[96:99], v144, s[56:57] nt
	global_load_dwordx4 v[100:103], v145, s[56:57] nt
	global_load_dwordx4 v[104:107], v146, s[56:57] nt
	global_load_dwordx4 v[108:111], v147, s[56:57] nt
	global_load_dwordx4 v[112:115], v94, s[56:57] nt
	global_load_dwordx4 v[116:119], v95, s[56:57] nt
	global_load_dwordx4 v[120:123], v236, s[56:57] nt
	global_load_dwordx4 v[124:127], v237, s[56:57] nt
	s_add_u32 s56, s56, 0x10000
	s_addc_u32 s57, s57, 0
	ds_read2_b32 v[128:129], v61 offset0:160 offset1:164
	ds_read2_b32 v[130:131], v61 offset0:168 offset1:172
	ds_read2_b32 v[132:133], v61 offset0:176 offset1:180
	ds_read2_b32 v[134:135], v61 offset0:184 offset1:188
	ds_read2_b32 v[136:137], v71 offset0:160 offset1:164
	ds_read2_b32 v[138:139], v71 offset0:168 offset1:172
	ds_read2_b32 v[140:141], v71 offset0:176 offset1:180
	ds_read2_b32 v[142:143], v71 offset0:184 offset1:188
	s_waitcnt lgkmcnt(0)
	s_waitcnt vmcnt(23)
	v_mul_f32_e32 v50, v58, v136
	v_pk_fma_f32 v[8:9], v[72:73], v[128:129], v[8:9] op_sel_hi:[1,0,1]
	v_pk_fma_f32 v[10:11], v[74:75], v[128:129], v[10:11] op_sel_hi:[1,0,1]
	v_pk_mul_f32 v[84:85], v[12:13], v[50:51] op_sel_hi:[1,0]
	v_pk_mul_f32 v[86:87], v[14:15], v[50:51] op_sel_hi:[1,0]
	v_pk_fma_f32 v[72:73], v[44:45], v[72:73], v[84:85]
	v_pk_fma_f32 v[74:75], v[42:43], v[74:75], v[86:87]
	global_store_dwordx4 v144, v[72:75], s[58:59] nt
	s_waitcnt vmcnt(23)
	v_mul_f32_e32 v50, v58, v137
	v_pk_fma_f32 v[8:9], v[76:77], v[128:129], v[8:9] op_sel:[0,1,0] op_sel_hi:[1,1,1]
	v_pk_fma_f32 v[10:11], v[78:79], v[128:129], v[10:11] op_sel:[0,1,0] op_sel_hi:[1,1,1]
	v_pk_mul_f32 v[84:85], v[12:13], v[50:51] op_sel_hi:[1,0]
	v_pk_mul_f32 v[86:87], v[14:15], v[50:51] op_sel_hi:[1,0]
	v_pk_fma_f32 v[76:77], v[44:45], v[76:77], v[84:85]
	v_pk_fma_f32 v[78:79], v[42:43], v[78:79], v[86:87]
	global_store_dwordx4 v145, v[76:79], s[58:59] nt
	s_waitcnt vmcnt(23)
	v_mul_f32_e32 v50, v58, v138
	v_pk_fma_f32 v[8:9], v[80:81], v[130:131], v[8:9] op_sel_hi:[1,0,1]
	v_pk_fma_f32 v[10:11], v[82:83], v[130:131], v[10:11] op_sel_hi:[1,0,1]
	v_pk_mul_f32 v[84:85], v[12:13], v[50:51] op_sel_hi:[1,0]
	v_pk_mul_f32 v[86:87], v[14:15], v[50:51] op_sel_hi:[1,0]
	v_pk_fma_f32 v[80:81], v[44:45], v[80:81], v[84:85]
	v_pk_fma_f32 v[82:83], v[42:43], v[82:83], v[86:87]
	global_store_dwordx4 v146, v[80:83], s[58:59] nt
	s_waitcnt vmcnt(23)
	v_mul_f32_e32 v50, v58, v139
	v_pk_fma_f32 v[8:9], v[32:33], v[130:131], v[8:9] op_sel:[0,1,0] op_sel_hi:[1,1,1]
	v_pk_fma_f32 v[10:11], v[34:35], v[130:131], v[10:11] op_sel:[0,1,0] op_sel_hi:[1,1,1]
	v_pk_mul_f32 v[84:85], v[12:13], v[50:51] op_sel_hi:[1,0]
	v_pk_mul_f32 v[86:87], v[14:15], v[50:51] op_sel_hi:[1,0]
	v_pk_fma_f32 v[32:33], v[44:45], v[32:33], v[84:85]
	v_pk_fma_f32 v[34:35], v[42:43], v[34:35], v[86:87]
	global_store_dwordx4 v147, v[32:35], s[58:59] nt
	s_waitcnt vmcnt(23)
	v_mul_f32_e32 v50, v58, v140
	v_pk_fma_f32 v[8:9], v[28:29], v[132:133], v[8:9] op_sel_hi:[1,0,1]
	v_pk_fma_f32 v[10:11], v[30:31], v[132:133], v[10:11] op_sel_hi:[1,0,1]
	v_pk_mul_f32 v[84:85], v[12:13], v[50:51] op_sel_hi:[1,0]
	v_pk_mul_f32 v[86:87], v[14:15], v[50:51] op_sel_hi:[1,0]
	v_pk_fma_f32 v[28:29], v[44:45], v[28:29], v[84:85]
	v_pk_fma_f32 v[30:31], v[42:43], v[30:31], v[86:87]
	global_store_dwordx4 v94, v[28:31], s[58:59] nt
	s_waitcnt vmcnt(23)
	v_mul_f32_e32 v50, v58, v141
	v_pk_fma_f32 v[8:9], v[24:25], v[132:133], v[8:9] op_sel:[0,1,0] op_sel_hi:[1,1,1]
	v_pk_fma_f32 v[10:11], v[26:27], v[132:133], v[10:11] op_sel:[0,1,0] op_sel_hi:[1,1,1]
	v_pk_mul_f32 v[84:85], v[12:13], v[50:51] op_sel_hi:[1,0]
	v_pk_mul_f32 v[86:87], v[14:15], v[50:51] op_sel_hi:[1,0]
	v_pk_fma_f32 v[24:25], v[44:45], v[24:25], v[84:85]
	v_pk_fma_f32 v[26:27], v[42:43], v[26:27], v[86:87]
	global_store_dwordx4 v95, v[24:27], s[58:59] nt
	s_waitcnt vmcnt(23)
	v_mul_f32_e32 v50, v58, v142
	v_pk_fma_f32 v[8:9], v[20:21], v[134:135], v[8:9] op_sel_hi:[1,0,1]
	v_pk_fma_f32 v[10:11], v[22:23], v[134:135], v[10:11] op_sel_hi:[1,0,1]
	v_pk_mul_f32 v[84:85], v[12:13], v[50:51] op_sel_hi:[1,0]
	v_pk_mul_f32 v[86:87], v[14:15], v[50:51] op_sel_hi:[1,0]
	v_pk_fma_f32 v[20:21], v[44:45], v[20:21], v[84:85]
	v_pk_fma_f32 v[22:23], v[42:43], v[22:23], v[86:87]
	global_store_dwordx4 v236, v[20:23], s[58:59] nt
	s_waitcnt vmcnt(23)
	v_mul_f32_e32 v50, v58, v143
	v_pk_fma_f32 v[8:9], v[16:17], v[134:135], v[8:9] op_sel:[0,1,0] op_sel_hi:[1,1,1]
	v_pk_fma_f32 v[10:11], v[18:19], v[134:135], v[10:11] op_sel:[0,1,0] op_sel_hi:[1,1,1]
	v_pk_mul_f32 v[84:85], v[12:13], v[50:51] op_sel_hi:[1,0]
	v_pk_mul_f32 v[86:87], v[14:15], v[50:51] op_sel_hi:[1,0]
	v_pk_fma_f32 v[16:17], v[44:45], v[16:17], v[84:85]
	v_pk_fma_f32 v[18:19], v[42:43], v[18:19], v[86:87]
	global_store_dwordx4 v237, v[16:19], s[58:59] nt
	s_add_u32 s58, s58, 0x10000
	s_addc_u32 s59, s59, 0
	global_load_dwordx4 v[72:75], v144, s[56:57] nt
	global_load_dwordx4 v[76:79], v145, s[56:57] nt
	global_load_dwordx4 v[80:83], v146, s[56:57] nt
	global_load_dwordx4 v[32:35], v147, s[56:57] nt
	global_load_dwordx4 v[28:31], v94, s[56:57] nt
	global_load_dwordx4 v[24:27], v95, s[56:57] nt
	global_load_dwordx4 v[20:23], v236, s[56:57] nt
	global_load_dwordx4 v[16:19], v237, s[56:57] nt
	s_add_u32 s56, s56, 0x10000
	s_addc_u32 s57, s57, 0
	ds_read2_b32 v[128:129], v61 offset0:192 offset1:196
	ds_read2_b32 v[130:131], v61 offset0:200 offset1:204
	ds_read2_b32 v[132:133], v61 offset0:208 offset1:212
	ds_read2_b32 v[134:135], v61 offset0:216 offset1:220
	ds_read2_b32 v[136:137], v71 offset0:192 offset1:196
	ds_read2_b32 v[138:139], v71 offset0:200 offset1:204
	ds_read2_b32 v[140:141], v71 offset0:208 offset1:212
	ds_read2_b32 v[142:143], v71 offset0:216 offset1:220
	s_waitcnt lgkmcnt(0)
	s_waitcnt vmcnt(23)
	v_mul_f32_e32 v50, v58, v136
	v_pk_fma_f32 v[8:9], v[96:97], v[128:129], v[8:9] op_sel_hi:[1,0,1]
	v_pk_fma_f32 v[10:11], v[98:99], v[128:129], v[10:11] op_sel_hi:[1,0,1]
	v_pk_mul_f32 v[84:85], v[12:13], v[50:51] op_sel_hi:[1,0]
	v_pk_mul_f32 v[86:87], v[14:15], v[50:51] op_sel_hi:[1,0]
	v_pk_fma_f32 v[96:97], v[44:45], v[96:97], v[84:85]
	v_pk_fma_f32 v[98:99], v[42:43], v[98:99], v[86:87]
	global_store_dwordx4 v144, v[96:99], s[58:59] nt
	s_waitcnt vmcnt(23)
	v_mul_f32_e32 v50, v58, v137
	v_pk_fma_f32 v[8:9], v[100:101], v[128:129], v[8:9] op_sel:[0,1,0] op_sel_hi:[1,1,1]
	v_pk_fma_f32 v[10:11], v[102:103], v[128:129], v[10:11] op_sel:[0,1,0] op_sel_hi:[1,1,1]
	v_pk_mul_f32 v[84:85], v[12:13], v[50:51] op_sel_hi:[1,0]
	v_pk_mul_f32 v[86:87], v[14:15], v[50:51] op_sel_hi:[1,0]
	v_pk_fma_f32 v[100:101], v[44:45], v[100:101], v[84:85]
	v_pk_fma_f32 v[102:103], v[42:43], v[102:103], v[86:87]
	global_store_dwordx4 v145, v[100:103], s[58:59] nt
	s_waitcnt vmcnt(23)
	v_mul_f32_e32 v50, v58, v138
	v_pk_fma_f32 v[8:9], v[104:105], v[130:131], v[8:9] op_sel_hi:[1,0,1]
	v_pk_fma_f32 v[10:11], v[106:107], v[130:131], v[10:11] op_sel_hi:[1,0,1]
	v_pk_mul_f32 v[84:85], v[12:13], v[50:51] op_sel_hi:[1,0]
	v_pk_mul_f32 v[86:87], v[14:15], v[50:51] op_sel_hi:[1,0]
	v_pk_fma_f32 v[104:105], v[44:45], v[104:105], v[84:85]
	v_pk_fma_f32 v[106:107], v[42:43], v[106:107], v[86:87]
	global_store_dwordx4 v146, v[104:107], s[58:59] nt
	s_waitcnt vmcnt(23)
	v_mul_f32_e32 v50, v58, v139
	v_pk_fma_f32 v[8:9], v[108:109], v[130:131], v[8:9] op_sel:[0,1,0] op_sel_hi:[1,1,1]
	v_pk_fma_f32 v[10:11], v[110:111], v[130:131], v[10:11] op_sel:[0,1,0] op_sel_hi:[1,1,1]
	v_pk_mul_f32 v[84:85], v[12:13], v[50:51] op_sel_hi:[1,0]
	v_pk_mul_f32 v[86:87], v[14:15], v[50:51] op_sel_hi:[1,0]
	v_pk_fma_f32 v[108:109], v[44:45], v[108:109], v[84:85]
	v_pk_fma_f32 v[110:111], v[42:43], v[110:111], v[86:87]
	global_store_dwordx4 v147, v[108:111], s[58:59] nt
	s_waitcnt vmcnt(23)
	v_mul_f32_e32 v50, v58, v140
	v_pk_fma_f32 v[8:9], v[112:113], v[132:133], v[8:9] op_sel_hi:[1,0,1]
	v_pk_fma_f32 v[10:11], v[114:115], v[132:133], v[10:11] op_sel_hi:[1,0,1]
	v_pk_mul_f32 v[84:85], v[12:13], v[50:51] op_sel_hi:[1,0]
	v_pk_mul_f32 v[86:87], v[14:15], v[50:51] op_sel_hi:[1,0]
	v_pk_fma_f32 v[112:113], v[44:45], v[112:113], v[84:85]
	v_pk_fma_f32 v[114:115], v[42:43], v[114:115], v[86:87]
	global_store_dwordx4 v94, v[112:115], s[58:59] nt
	s_waitcnt vmcnt(23)
	v_mul_f32_e32 v50, v58, v141
	v_pk_fma_f32 v[8:9], v[116:117], v[132:133], v[8:9] op_sel:[0,1,0] op_sel_hi:[1,1,1]
	v_pk_fma_f32 v[10:11], v[118:119], v[132:133], v[10:11] op_sel:[0,1,0] op_sel_hi:[1,1,1]
	v_pk_mul_f32 v[84:85], v[12:13], v[50:51] op_sel_hi:[1,0]
	v_pk_mul_f32 v[86:87], v[14:15], v[50:51] op_sel_hi:[1,0]
	v_pk_fma_f32 v[116:117], v[44:45], v[116:117], v[84:85]
	v_pk_fma_f32 v[118:119], v[42:43], v[118:119], v[86:87]
	global_store_dwordx4 v95, v[116:119], s[58:59] nt
	s_waitcnt vmcnt(23)
	v_mul_f32_e32 v50, v58, v142
	v_pk_fma_f32 v[8:9], v[120:121], v[134:135], v[8:9] op_sel_hi:[1,0,1]
	v_pk_fma_f32 v[10:11], v[122:123], v[134:135], v[10:11] op_sel_hi:[1,0,1]
	v_pk_mul_f32 v[84:85], v[12:13], v[50:51] op_sel_hi:[1,0]
	v_pk_mul_f32 v[86:87], v[14:15], v[50:51] op_sel_hi:[1,0]
	v_pk_fma_f32 v[120:121], v[44:45], v[120:121], v[84:85]
	v_pk_fma_f32 v[122:123], v[42:43], v[122:123], v[86:87]
	global_store_dwordx4 v236, v[120:123], s[58:59] nt
	s_waitcnt vmcnt(23)
	v_mul_f32_e32 v50, v58, v143
	v_pk_fma_f32 v[8:9], v[124:125], v[134:135], v[8:9] op_sel:[0,1,0] op_sel_hi:[1,1,1]
	v_pk_fma_f32 v[10:11], v[126:127], v[134:135], v[10:11] op_sel:[0,1,0] op_sel_hi:[1,1,1]
	v_pk_mul_f32 v[84:85], v[12:13], v[50:51] op_sel_hi:[1,0]
	v_pk_mul_f32 v[86:87], v[14:15], v[50:51] op_sel_hi:[1,0]
	v_pk_fma_f32 v[124:125], v[44:45], v[124:125], v[84:85]
	v_pk_fma_f32 v[126:127], v[42:43], v[126:127], v[86:87]
	global_store_dwordx4 v237, v[124:127], s[58:59] nt
	s_add_u32 s58, s58, 0x10000
	s_addc_u32 s59, s59, 0
	ds_read2_b32 v[128:129], v61 offset0:224 offset1:228
	ds_read2_b32 v[130:131], v61 offset0:232 offset1:236
	ds_read2_b32 v[132:133], v61 offset0:240 offset1:244
	ds_read2_b32 v[134:135], v61 offset0:248 offset1:252
	ds_read2_b32 v[136:137], v71 offset0:224 offset1:228
	ds_read2_b32 v[138:139], v71 offset0:232 offset1:236
	ds_read2_b32 v[140:141], v71 offset0:240 offset1:244
	ds_read2_b32 v[142:143], v71 offset0:248 offset1:252
	s_waitcnt lgkmcnt(0)
	s_waitcnt vmcnt(15)
	v_mul_f32_e32 v50, v58, v136
	v_pk_fma_f32 v[8:9], v[72:73], v[128:129], v[8:9] op_sel_hi:[1,0,1]
	v_pk_fma_f32 v[10:11], v[74:75], v[128:129], v[10:11] op_sel_hi:[1,0,1]
	v_pk_mul_f32 v[84:85], v[12:13], v[50:51] op_sel_hi:[1,0]
	v_pk_mul_f32 v[86:87], v[14:15], v[50:51] op_sel_hi:[1,0]
	v_pk_fma_f32 v[72:73], v[44:45], v[72:73], v[84:85]
	v_pk_fma_f32 v[74:75], v[42:43], v[74:75], v[86:87]
	global_store_dwordx4 v144, v[72:75], s[58:59] nt
	s_waitcnt vmcnt(15)
	v_mul_f32_e32 v50, v58, v137
	v_pk_fma_f32 v[8:9], v[76:77], v[128:129], v[8:9] op_sel:[0,1,0] op_sel_hi:[1,1,1]
	v_pk_fma_f32 v[10:11], v[78:79], v[128:129], v[10:11] op_sel:[0,1,0] op_sel_hi:[1,1,1]
	v_pk_mul_f32 v[84:85], v[12:13], v[50:51] op_sel_hi:[1,0]
	v_pk_mul_f32 v[86:87], v[14:15], v[50:51] op_sel_hi:[1,0]
	v_pk_fma_f32 v[76:77], v[44:45], v[76:77], v[84:85]
	v_pk_fma_f32 v[78:79], v[42:43], v[78:79], v[86:87]
	global_store_dwordx4 v145, v[76:79], s[58:59] nt
	s_waitcnt vmcnt(15)
	v_mul_f32_e32 v50, v58, v138
	v_pk_fma_f32 v[8:9], v[80:81], v[130:131], v[8:9] op_sel_hi:[1,0,1]
	v_pk_fma_f32 v[10:11], v[82:83], v[130:131], v[10:11] op_sel_hi:[1,0,1]
	v_pk_mul_f32 v[84:85], v[12:13], v[50:51] op_sel_hi:[1,0]
	v_pk_mul_f32 v[86:87], v[14:15], v[50:51] op_sel_hi:[1,0]
	v_pk_fma_f32 v[80:81], v[44:45], v[80:81], v[84:85]
	v_pk_fma_f32 v[82:83], v[42:43], v[82:83], v[86:87]
	global_store_dwordx4 v146, v[80:83], s[58:59] nt
	s_waitcnt vmcnt(15)
	v_mul_f32_e32 v50, v58, v139
	v_pk_fma_f32 v[8:9], v[32:33], v[130:131], v[8:9] op_sel:[0,1,0] op_sel_hi:[1,1,1]
	v_pk_fma_f32 v[10:11], v[34:35], v[130:131], v[10:11] op_sel:[0,1,0] op_sel_hi:[1,1,1]
	v_pk_mul_f32 v[84:85], v[12:13], v[50:51] op_sel_hi:[1,0]
	v_pk_mul_f32 v[86:87], v[14:15], v[50:51] op_sel_hi:[1,0]
	v_pk_fma_f32 v[32:33], v[44:45], v[32:33], v[84:85]
	v_pk_fma_f32 v[34:35], v[42:43], v[34:35], v[86:87]
	global_store_dwordx4 v147, v[32:35], s[58:59] nt
	s_waitcnt vmcnt(15)
	v_mul_f32_e32 v50, v58, v140
	v_pk_fma_f32 v[8:9], v[28:29], v[132:133], v[8:9] op_sel_hi:[1,0,1]
	v_pk_fma_f32 v[10:11], v[30:31], v[132:133], v[10:11] op_sel_hi:[1,0,1]
	v_pk_mul_f32 v[84:85], v[12:13], v[50:51] op_sel_hi:[1,0]
	v_pk_mul_f32 v[86:87], v[14:15], v[50:51] op_sel_hi:[1,0]
	v_pk_fma_f32 v[28:29], v[44:45], v[28:29], v[84:85]
	v_pk_fma_f32 v[30:31], v[42:43], v[30:31], v[86:87]
	global_store_dwordx4 v94, v[28:31], s[58:59] nt
	s_waitcnt vmcnt(15)
	v_mul_f32_e32 v50, v58, v141
	v_pk_fma_f32 v[8:9], v[24:25], v[132:133], v[8:9] op_sel:[0,1,0] op_sel_hi:[1,1,1]
	v_pk_fma_f32 v[10:11], v[26:27], v[132:133], v[10:11] op_sel:[0,1,0] op_sel_hi:[1,1,1]
	v_pk_mul_f32 v[84:85], v[12:13], v[50:51] op_sel_hi:[1,0]
	v_pk_mul_f32 v[86:87], v[14:15], v[50:51] op_sel_hi:[1,0]
	v_pk_fma_f32 v[24:25], v[44:45], v[24:25], v[84:85]
	v_pk_fma_f32 v[26:27], v[42:43], v[26:27], v[86:87]
	global_store_dwordx4 v95, v[24:27], s[58:59] nt
	s_waitcnt vmcnt(15)
	v_mul_f32_e32 v50, v58, v142
	v_pk_fma_f32 v[8:9], v[20:21], v[134:135], v[8:9] op_sel_hi:[1,0,1]
	v_pk_fma_f32 v[10:11], v[22:23], v[134:135], v[10:11] op_sel_hi:[1,0,1]
	v_pk_mul_f32 v[84:85], v[12:13], v[50:51] op_sel_hi:[1,0]
	v_pk_mul_f32 v[86:87], v[14:15], v[50:51] op_sel_hi:[1,0]
	v_pk_fma_f32 v[20:21], v[44:45], v[20:21], v[84:85]
	v_pk_fma_f32 v[22:23], v[42:43], v[22:23], v[86:87]
	global_store_dwordx4 v236, v[20:23], s[58:59] nt
	s_waitcnt vmcnt(15)
	v_mul_f32_e32 v50, v58, v143
	v_pk_fma_f32 v[8:9], v[16:17], v[134:135], v[8:9] op_sel:[0,1,0] op_sel_hi:[1,1,1]
	v_pk_fma_f32 v[10:11], v[18:19], v[134:135], v[10:11] op_sel:[0,1,0] op_sel_hi:[1,1,1]
	v_pk_mul_f32 v[84:85], v[12:13], v[50:51] op_sel_hi:[1,0]
	v_pk_mul_f32 v[86:87], v[14:15], v[50:51] op_sel_hi:[1,0]
	v_pk_fma_f32 v[16:17], v[44:45], v[16:17], v[84:85]
	v_pk_fma_f32 v[18:19], v[42:43], v[18:19], v[86:87]
	global_store_dwordx4 v237, v[16:19], s[58:59] nt
	s_add_u32 s58, s58, 0x10000
	s_addc_u32 s59, s59, 0
	s_nop 0
	v_lshl_add_u32 v16, v40, 4, 0
	ds_write_b128 v16, v[8:11] offset:5376
	v_cmp_gt_u32_e32 vcc, s43, v40
	v_mov_b32_e32 v8, 0
	s_waitcnt lgkmcnt(0)
	s_barrier
	s_and_saveexec_b64 s[24:25], vcc
	s_cbranch_execz .LBB0_2062
	v_add_f32_e32 v0, v0, v1
	v_add_f32_e32 v1, v2, v3
	v_add_f32_e32 v0, v0, v1
	v_mul_f32_e32 v1, 0xbfb8aa3b, v39
	v_add_f32_e32 v4, v4, v5
	v_add_f32_e32 v5, v6, v7
	v_exp_f32_e32 v1, v1
	v_add_f32_e32 v4, v4, v5
	v_mul_f32_e32 v8, v4, v58
	v_fma_f32 v0, v0, v42, v8
	v_max_f32_e64 v0, |v0|, v1
	v_div_scale_f32 v1, s[52:53], v0, v0, 1.0
	v_rcp_f32_e32 v2, v1
	v_mov_b32_e32 v43, v42
	s_lshl_b64 s[52:53], s[2:3], 12
	s_add_u32 s27, s30, s52
	v_fma_f32 v3, -v1, v2, 1.0
	v_fmac_f32_e32 v2, v3, v2
	v_div_scale_f32 v3, vcc, 1.0, v0, 1.0
	v_mul_f32_e32 v4, v3, v2
	v_fma_f32 v5, -v1, v4, v3
	v_fmac_f32_e32 v4, v5, v2
	v_fma_f32 v1, -v1, v4, v3
	v_div_fmas_f32 v1, v1, v2, v4
	v_div_fixup_f32 v10, v1, v0, 1.0
	v_lshl_add_u32 v0, v60, 4, 0
	ds_read_b128 v[0:3], v0 offset:5376
	ds_read_b128 v[4:7], v16 offset:7424
	s_addc_u32 s29, s31, s53
	s_lshl_b32 s26, s26, 1
	s_add_u32 s26, s27, s26
	s_addc_u32 s27, s29, 0
	s_waitcnt lgkmcnt(0)
	v_pk_add_f32 v[18:19], v[2:3], v[6:7]
	v_pk_add_f32 v[20:21], v[0:1], v[4:5]
	ds_read_b128 v[0:3], v16 offset:9472
	ds_read_b128 v[4:7], v16 offset:11520
	s_waitcnt lgkmcnt(0)
	v_pk_add_f32 v[2:3], v[2:3], v[6:7]
	v_pk_add_f32 v[0:1], v[0:1], v[4:5]
	v_pk_add_f32 v[2:3], v[18:19], v[2:3]
	v_pk_add_f32 v[0:1], v[20:21], v[0:1]
	v_pk_mul_f32 v[2:3], v[42:43], v[2:3]
	v_pk_mul_f32 v[0:1], v[44:45], v[0:1]
	v_pk_fma_f32 v[2:3], v[14:15], v[8:9], v[2:3] op_sel_hi:[1,0,1]
	v_pk_fma_f32 v[0:1], v[12:13], v[8:9], v[0:1] op_sel_hi:[1,0,1]
	v_pk_mul_f32 v[2:3], v[10:11], v[2:3] op_sel_hi:[0,1]
	v_pk_mul_f32 v[0:1], v[10:11], v[0:1] op_sel_hi:[0,1]
	v_pk_mul_f32 v[4:5], v[2:3], v[2:3]
	v_pk_mul_f32 v[6:7], v[0:1], v[0:1]
	v_cvt_pk_bf16_f32 v0, v0, v1
	v_pk_mov_b32 v[8:9], v[6:7], v[4:5] op_sel:[1,0]
	v_mov_b32_e32 v7, v5
	v_pk_add_f32 v[4:5], v[8:9], v[6:7]
	v_cvt_pk_bf16_f32 v1, v2, v3
	v_add_f32_e32 v8, v4, v5
	v_lshlrev_b32_e32 v2, 1, v59
	global_store_dwordx2 v2, v[0:1], s[26:27]

.LBB0_2071:
	s_cmp_eq_u32 s98, 0
	s_cbranch_scc0 .Learly_exit
	s_waitcnt vmcnt(0)
	s_waitcnt lgkmcnt(0)
	s_barrier
	s_mov_b64 s[0:1], exec
	v_readlane_b32 s2, v234, 20
	v_readlane_b32 s3, v234, 21
	s_and_b64 s[2:3], s[0:1], s[2:3]
	s_mov_b64 exec, s[2:3]
	s_cbranch_execz .LBB0_2123
	s_add_i32 s2, 0, 0x27ff0
	v_mov_b32_e32 v0, s2
	s_waitcnt vmcnt(0) expcnt(0) lgkmcnt(0)
	ds_read_b32 v2, v0
	s_add_i32 s2, 0, 0x27ff4
	v_mov_b32_e32 v0, s2
	ds_read_b32 v0, v0
	s_waitcnt lgkmcnt(1)
	v_cmp_ne_u32_e32 vcc, 0, v2
	s_cbranch_vccnz .LBB0_2087
	v_readlane_b32 s2, v234, 12
	v_readlane_b32 s3, v234, 13
	v_readlane_b32 s4, v234, 16
	v_readlane_b32 s36, v234, 0
	s_mul_i32 s47, s3, s4
	v_readlane_b32 s38, v234, 2
	s_mul_i32 s47, s47, s2
	v_readlane_b32 s39, v234, 3
	s_add_u32 s2, s38, 0x100200
	s_addc_u32 s3, s39, 0
	s_add_u32 s4, s38, 0x100400
	s_addc_u32 s5, s39, 0
	s_add_u32 s6, s38, 0x100500
	s_addc_u32 s7, s39, 0
	s_add_u32 s8, s38, 0x100600
	s_addc_u32 s9, s39, 0
	s_add_u32 s10, s38, 0x100700
	s_addc_u32 s11, s39, 0
	s_add_u32 s12, s38, 0x100800
	s_addc_u32 s13, s39, 0
	s_add_u32 s14, s38, 0x100900
	s_addc_u32 s15, s39, 0
	s_add_u32 s16, s38, 0x100a00
	s_addc_u32 s17, s39, 0
	s_add_u32 s18, s38, 0x100b00
	s_addc_u32 s19, s39, 0
	s_add_u32 s20, s38, 0x100c00
	s_addc_u32 s21, s39, 0
	s_add_u32 s22, s38, 0x100d00
	s_addc_u32 s23, s39, 0
	s_add_u32 s24, s38, 0x100e00
	s_addc_u32 s25, s39, 0
	s_add_u32 s26, s38, 0x100f00
	s_addc_u32 s27, s39, 0
	s_add_u32 s28, s38, 0x101000
	s_addc_u32 s29, s39, 0
	s_add_u32 s30, s38, 0x101100
	s_addc_u32 s31, s39, 0
	s_add_u32 s34, s38, 0x101200
	s_addc_u32 s35, s39, 0
	v_readlane_b32 s37, v234, 1
	s_add_u32 s36, s38, 0x101300
	s_addc_u32 s37, s39, 0
	s_mov_b32 s48, 1
	v_mov_b32_e32 v16, 0
	s_branch .LBB0_2075

	.amdhsa_kernel _Z10hybrid_fwd4Args
		.amdhsa_group_segment_fixed_size 0
		.amdhsa_private_segment_fixed_size 0
		.amdhsa_kernarg_size 496
		.amdhsa_user_sgpr_count 2
		.amdhsa_user_sgpr_dispatch_ptr 0
		.amdhsa_user_sgpr_queue_ptr 0
		.amdhsa_user_sgpr_kernarg_segment_ptr 1
		.amdhsa_user_sgpr_dispatch_id 0
		.amdhsa_user_sgpr_kernarg_preload_length 0
		.amdhsa_user_sgpr_kernarg_preload_offset 0
		.amdhsa_user_sgpr_private_segment_size 0
		.amdhsa_uses_dynamic_stack 0
		.amdhsa_enable_private_segment 0
		.amdhsa_system_sgpr_workgroup_id_x 1
		.amdhsa_system_sgpr_workgroup_id_y 0
		.amdhsa_system_sgpr_workgroup_id_z 0
		.amdhsa_system_sgpr_workgroup_info 0
		.amdhsa_system_vgpr_workitem_id 2
		.amdhsa_next_free_vgpr 256
		.amdhsa_next_free_sgpr 99
		.amdhsa_accum_offset 256
		.amdhsa_reserve_vcc 1
		.amdhsa_float_round_mode_32 0
		.amdhsa_float_round_mode_16_64 0
		.amdhsa_float_denorm_mode_32 3
		.amdhsa_float_denorm_mode_16_64 3
		.amdhsa_dx10_clamp 1
		.amdhsa_ieee_mode 1
		.amdhsa_fp16_overflow 0
		.amdhsa_tg_split 0
		.amdhsa_exception_fp_ieee_invalid_op 0
		.amdhsa_exception_fp_denorm_src 0
		.amdhsa_exception_fp_ieee_div_zero 0
		.amdhsa_exception_fp_ieee_overflow 0
		.amdhsa_exception_fp_ieee_underflow 0
		.amdhsa_exception_fp_ieee_inexact 0
		.amdhsa_exception_int_div_zero 0
	.end_amdhsa_kernel

amdhsa.kernels:
  - .agpr_count:     0
    .args:
      - .offset:         0
        .size:           240
        .value_kind:     by_value
      - .offset:         240
        .size:           4
        .value_kind:     hidden_block_count_x
      - .offset:         244
        .size:           4
        .value_kind:     hidden_block_count_y
      - .offset:         248
        .size:           4
        .value_kind:     hidden_block_count_z
      - .offset:         252
        .size:           2
        .value_kind:     hidden_group_size_x
      - .offset:         254
        .size:           2
        .value_kind:     hidden_group_size_y
      - .offset:         256
        .size:           2
        .value_kind:     hidden_group_size_z
      - .offset:         258
        .size:           2
        .value_kind:     hidden_remainder_x
      - .offset:         260
        .size:           2
        .value_kind:     hidden_remainder_y
      - .offset:         262
        .size:           2
        .value_kind:     hidden_remainder_z
      - .offset:         280
        .size:           8
        .value_kind:     hidden_global_offset_x
      - .offset:         288
        .size:           8
        .value_kind:     hidden_global_offset_y
      - .offset:         296
        .size:           8
        .value_kind:     hidden_global_offset_z
      - .offset:         304
        .size:           2
        .value_kind:     hidden_grid_dims
      - .offset:         328
        .size:           8
        .value_kind:     hidden_multigrid_sync_arg
      - .offset:         360
        .size:           4
        .value_kind:     hidden_dynamic_lds_size
    .group_segment_fixed_size: 0
    .kernarg_segment_align: 8
    .kernarg_segment_size: 496
    .language:       OpenCL C
    .language_version:
      - 2
      - 0
    .max_flat_workgroup_size: 512
    .name:           _Z10hybrid_fwd4Args
    .private_segment_fixed_size: 0
    .sgpr_count:     105
    .sgpr_spill_count: 170
    .symbol:         _Z10hybrid_fwd4Args.kd
    .uniform_work_group_size: 1
    .uses_dynamic_stack: false
    .vgpr_count:     256
    .vgpr_spill_count: 0
    .wavefront_size: 64
